# additionally: LDS-DMA tile loads in five of the GEMM K-loops use the scalar-base + 32-bit lane offset form (no v_lshl_add_u64 address math in the load segments)
# baseline (speedup 1.0000x reference)
; #define PG8_STAGE(bufoff, gbase, voff) do { _Pragma("unroll") for (int _i = 0; _i < 2; ++_i) \
;         __builtin_amdgcn_global_load_lds((const unsigned*)((const char*)(gbase) + (voff)[_i]), (PG8_LAS unsigned*)(lds + (bufoff) + ldsw + _i * 8192), 16, 0, 0); } while (0)
; #define PG8_LDA(dst, b, h) do { _Pragma("unroll") for (int m = 0; m < 4; ++m) _Pragma("unroll") for (int k = 0; k < 2; ++k) dst[m][k] = *(const PG8_LAS bf16x8*)(lds + PG8_SA(b, h) + aoff + m * 2048 + k * 1024); } while (0)
; #define PG8_LDB(dst, b, h) do { _Pragma("unroll") for (int n = 0; n < 2; ++n) _Pragma("unroll") for (int k = 0; k < 2; ++k) dst[n][k] = *(const PG8_LAS bf16x8*)(lds + PG8_SB(b, h) + boff + n * 2048 + k * 1024); } while (0)
; #define PG8_MMA(ai, bj, At, Bt) do { __builtin_amdgcn_s_setprio(1); _Pragma("unroll") for (int m = 0; m < 4; ++m) _Pragma("unroll") for (int n = 0; n < 2; ++n) _Pragma("unroll") for (int k = 0; k < 2; ++k) \
;         acc[ai][bj][m][n] = __builtin_amdgcn_mfma_f32_16x16x32_bf16(Bt[n][k], At[m][k], acc[ai][bj][m][n], 0, 0, 0); __builtin_amdgcn_s_setprio(0); } while (0)
; #define PG8_WAIT_V(n) asm volatile("s_waitcnt vmcnt(" #n ")" ::: "memory")
; #define PG8_WAIT_L(n) asm volatile("s_waitcnt lgkmcnt(" #n ")" ::: "memory")
; #define PG8_BAR __builtin_amdgcn_s_barrier()
; #define PG8_SCHED __builtin_amdgcn_sched_barrier(0)
; template <class Epi, class Sched, bool ALIGN_EPI = false, bool SP2 = false>
; __device__ __forceinline__ void gemm_phase(PG8_LAS unsigned char* lds, const Gemm g, const Sched& S, const Epi& E) {
;     ...
;             const bool last = (t == nt - 2);
;             const char* a1 = cA + (size_t)(t + 1) * kstep;
;             const char* a2 = last ? nA : cA + (size_t)(t + 2) * kstep; const char* b2 = last ? nB : cB + (size_t)(t + 2) * kstep;
;             const char* a3 = a2 + kstep; const char* b3 = b2 + kstep;
;             if (last && has_next) S.a_ready(nxt);
;             if constexpr (SP2) {
;             PG8_LDB(B0, 0, 0); PG8_LDB(B1, 0, 1); PG8_SCHED; PG8_LDA(At, 0, 0); PG8_STAGE(PG8_SA(1, 1), a1 + hstep, voffA);
;             PG8_WAIT_V(8); PG8_WAIT_L(0); PG8_BAR; PG8_MMA(0, 0, At, B0); PG8_MMA(0, 1, At, B1); PG8_BAR; PG8_SCHED;
;             PG8_LDA(At, 0, 1); PG8_STAGE(PG8_SB(0, 0), b2, voffB); PG8_STAGE(PG8_SB(0, 1), b2 + hstep, voffB); PG8_STAGE(PG8_SA(0, 0), a2, voffA);
.LBB0_162:
	s_add_u32 s10, s44, 0xfffc0080
	s_addc_u32 s11, s45, -1
	s_add_i32 s60, 16, 0x10000
	s_cmp_eq_u32 s59, 12
	s_cselect_b32 s49, s27, s11
	s_cselect_b32 s48, s34, s10
	s_cselect_b32 s47, s25, s58
	s_cselect_b32 s46, s35, s57
	s_add_i32 s10, 16, 0x14000
	v_add_u32_e32 v102, s60, v183
	v_add_u32_e32 v180, s10, v183
	ds_read_b128 v[90:93], v102
	ds_read_b128 v[94:97], v102 offset:1024
	ds_read_b128 v[98:101], v102 offset:2048
	ds_read_b128 v[102:105], v102 offset:3072
	ds_read_b128 v[158:161], v180
	ds_read_b128 v[176:179], v180 offset:1024
	ds_read_b128 v[186:189], v180 offset:2048
	ds_read_b128 v[190:193], v180 offset:3072
	s_add_i32 m0, s7, 0xc000
	ds_read_b128 v[194:197], v185
	ds_read_b128 v[198:201], v185 offset:1024
	ds_read_b128 v[202:205], v185 offset:2048
	ds_read_b128 v[206:209], v185 offset:3072
	ds_read_b128 v[210:213], v185 offset:4096
	ds_read_b128 v[214:217], v185 offset:5120
	ds_read_b128 v[218:221], v185 offset:6144
	ds_read_b128 v[222:225], v185 offset:7168
	global_load_lds_dwordx4 v156, s[44:45]
	s_add_i32 m0, s7, 0xe000
	s_nop 0
	global_load_lds_dwordx4 v154, s[44:45]
	s_waitcnt vmcnt(8)
	s_waitcnt lgkmcnt(0)
	s_setprio 1
	s_barrier
	v_mfma_f32_16x16x32_bf16 v[142:145], v[90:93], v[194:197], v[142:145]
	v_mfma_f32_16x16x32_bf16 v[138:141], v[98:101], v[194:197], v[138:141]
	v_mfma_f32_16x16x32_bf16 v[122:125], v[98:101], v[202:205], v[122:125]
	v_mfma_f32_16x16x32_bf16 v[126:129], v[90:93], v[202:205], v[126:129]
	v_mfma_f32_16x16x32_bf16 v[110:113], v[90:93], v[210:213], v[110:113]
	v_mfma_f32_16x16x32_bf16 v[106:109], v[98:101], v[210:213], v[106:109]
	v_mfma_f32_16x16x32_bf16 v[74:77], v[98:101], v[218:221], v[74:77]
	v_mfma_f32_16x16x32_bf16 v[78:81], v[90:93], v[218:221], v[78:81]
	v_mfma_f32_16x16x32_bf16 v[142:145], v[94:97], v[198:201], v[142:145]
	v_mfma_f32_16x16x32_bf16 v[138:141], v[102:105], v[198:201], v[138:141]
	v_mfma_f32_16x16x32_bf16 v[122:125], v[102:105], v[206:209], v[122:125]
	v_mfma_f32_16x16x32_bf16 v[126:129], v[94:97], v[206:209], v[126:129]
	v_mfma_f32_16x16x32_bf16 v[110:113], v[94:97], v[214:217], v[110:113]
	v_mfma_f32_16x16x32_bf16 v[106:109], v[102:105], v[214:217], v[106:109]
	v_mfma_f32_16x16x32_bf16 v[74:77], v[102:105], v[222:225], v[74:77]
	v_mfma_f32_16x16x32_bf16 v[78:81], v[94:97], v[222:225], v[78:81]
	v_mfma_f32_16x16x32_bf16 v[134:137], v[158:161], v[194:197], v[134:137]
	v_mfma_f32_16x16x32_bf16 v[130:133], v[186:189], v[194:197], v[130:133]
	v_mfma_f32_16x16x32_bf16 v[114:117], v[186:189], v[202:205], v[114:117]
	v_mfma_f32_16x16x32_bf16 v[118:121], v[158:161], v[202:205], v[118:121]
	v_mfma_f32_16x16x32_bf16 v[86:89], v[158:161], v[210:213], v[86:89]
	v_mfma_f32_16x16x32_bf16 v[82:85], v[186:189], v[210:213], v[82:85]
	v_mfma_f32_16x16x32_bf16 v[66:69], v[186:189], v[218:221], v[66:69]
	v_mfma_f32_16x16x32_bf16 v[70:73], v[158:161], v[218:221], v[70:73]
	v_mfma_f32_16x16x32_bf16 v[134:137], v[176:179], v[198:201], v[134:137]
	v_mfma_f32_16x16x32_bf16 v[130:133], v[190:193], v[198:201], v[130:133]
	v_mfma_f32_16x16x32_bf16 v[114:117], v[190:193], v[206:209], v[114:117]
	v_mfma_f32_16x16x32_bf16 v[118:121], v[176:179], v[206:209], v[118:121]
	v_mfma_f32_16x16x32_bf16 v[86:89], v[176:179], v[214:217], v[86:89]
	v_mfma_f32_16x16x32_bf16 v[82:85], v[190:193], v[214:217], v[82:85]
	v_mfma_f32_16x16x32_bf16 v[66:69], v[190:193], v[222:225], v[66:69]
	v_mfma_f32_16x16x32_bf16 v[70:73], v[176:179], v[222:225], v[70:73]
	s_barrier
	s_setprio 0
	s_add_i32 s11, s60, s6
	s_mov_b32 m0, s11
	ds_read_b128 v[194:197], v185 offset:16384
	ds_read_b128 v[198:201], v185 offset:17408
	ds_read_b128 v[202:205], v185 offset:18432
	ds_read_b128 v[206:209], v185 offset:19456
	ds_read_b128 v[210:213], v185 offset:20480
	ds_read_b128 v[214:217], v185 offset:21504
	ds_read_b128 v[218:221], v185 offset:22528
	ds_read_b128 v[222:225], v185 offset:23552
	global_load_lds_dwordx4 v0, s[46:47]
	s_add_i32 m0, s11, 0x2000
	s_add_u32 s60, s46, 0x40000
	v_lshl_add_u64 v[226:227], s[46:47], 0, v[146:147]
	s_addc_u32 s61, s47, 0
	s_add_i32 s10, s10, s6
	global_load_lds_dwordx4 v146, s[46:47]
	s_mov_b32 m0, s10
	v_lshl_add_u64 v[240:241], s[48:49], 0, v[148:149]
	s_nop 0
	global_load_lds_dwordx4 v0, s[60:61]
	s_add_i32 m0, s10, 0x2000
	s_nop 0
	global_load_lds_dwordx4 v146, s[60:61]
	v_lshl_add_u64 v[238:239], s[48:49], 0, v[150:151]
	s_mov_b32 m0, s7
	s_nop 0
	global_load_lds_dwordx4 v150, s[48:49]
	s_mov_b32 m0, s8
	s_nop 0
	global_load_lds_dwordx4 v148, s[48:49]
	s_waitcnt vmcnt(8)
	s_waitcnt lgkmcnt(0)
	s_setprio 1
	s_barrier
	v_mfma_f32_16x16x32_bf16 v[62:65], v[90:93], v[194:197], v[62:65]
	v_mfma_f32_16x16x32_bf16 v[58:61], v[98:101], v[194:197], v[58:61]
	v_mfma_f32_16x16x32_bf16 v[42:45], v[98:101], v[202:205], v[42:45]
	v_mfma_f32_16x16x32_bf16 v[46:49], v[90:93], v[202:205], v[46:49]
	v_mfma_f32_16x16x32_bf16 v[30:33], v[90:93], v[210:213], v[30:33]
	v_mfma_f32_16x16x32_bf16 v[26:29], v[98:101], v[210:213], v[26:29]
	v_mfma_f32_16x16x32_bf16 v[10:13], v[98:101], v[218:221], v[10:13]
	v_mfma_f32_16x16x32_bf16 v[14:17], v[90:93], v[218:221], v[14:17]
	v_mfma_f32_16x16x32_bf16 v[62:65], v[94:97], v[198:201], v[62:65]
	v_mfma_f32_16x16x32_bf16 v[58:61], v[102:105], v[198:201], v[58:61]
	v_mfma_f32_16x16x32_bf16 v[42:45], v[102:105], v[206:209], v[42:45]
	v_mfma_f32_16x16x32_bf16 v[46:49], v[94:97], v[206:209], v[46:49]
	v_mfma_f32_16x16x32_bf16 v[30:33], v[94:97], v[214:217], v[30:33]
	v_mfma_f32_16x16x32_bf16 v[26:29], v[102:105], v[214:217], v[26:29]
	v_mfma_f32_16x16x32_bf16 v[10:13], v[102:105], v[222:225], v[10:13]
	v_mfma_f32_16x16x32_bf16 v[14:17], v[94:97], v[222:225], v[14:17]
	v_mfma_f32_16x16x32_bf16 v[54:57], v[158:161], v[194:197], v[54:57]
	v_mfma_f32_16x16x32_bf16 v[50:53], v[186:189], v[194:197], v[50:53]
	v_mfma_f32_16x16x32_bf16 v[34:37], v[186:189], v[202:205], v[34:37]
	v_mfma_f32_16x16x32_bf16 v[38:41], v[158:161], v[202:205], v[38:41]
	v_mfma_f32_16x16x32_bf16 v[22:25], v[158:161], v[210:213], v[22:25]
	v_mfma_f32_16x16x32_bf16 v[18:21], v[186:189], v[210:213], v[18:21]
	v_mfma_f32_16x16x32_bf16 v[2:5], v[186:189], v[218:221], v[2:5]
	v_mfma_f32_16x16x32_bf16 v[6:9], v[158:161], v[218:221], v[6:9]
	v_mfma_f32_16x16x32_bf16 v[54:57], v[176:179], v[198:201], v[54:57]
	v_mfma_f32_16x16x32_bf16 v[50:53], v[190:193], v[198:201], v[50:53]
	v_mfma_f32_16x16x32_bf16 v[34:37], v[190:193], v[206:209], v[34:37]
	v_mfma_f32_16x16x32_bf16 v[38:41], v[176:179], v[206:209], v[38:41]
	v_mfma_f32_16x16x32_bf16 v[22:25], v[176:179], v[214:217], v[22:25]
	v_mfma_f32_16x16x32_bf16 v[18:21], v[190:193], v[214:217], v[18:21]
	v_mfma_f32_16x16x32_bf16 v[2:5], v[190:193], v[222:225], v[2:5]
	v_mfma_f32_16x16x32_bf16 v[6:9], v[176:179], v[222:225], v[6:9]
	s_barrier
; #define PG8_STAGE(bufoff, gbase, voff) do { _Pragma("unroll") for (int _i = 0; _i < 2; ++_i) \
;         __builtin_amdgcn_global_load_lds((const unsigned*)((const char*)(gbase) + (voff)[_i]), (PG8_LAS unsigned*)(lds + (bufoff) + ldsw + _i * 8192), 16, 0, 0); } while (0)
; #define PG8_LDA(dst, b, h) do { _Pragma("unroll") for (int m = 0; m < 4; ++m) _Pragma("unroll") for (int k = 0; k < 2; ++k) dst[m][k] = *(const PG8_LAS bf16x8*)(lds + PG8_SA(b, h) + aoff + m * 2048 + k * 1024); } while (0)
; #define PG8_LDB(dst, b, h) do { _Pragma("unroll") for (int n = 0; n < 2; ++n) _Pragma("unroll") for (int k = 0; k < 2; ++k) dst[n][k] = *(const PG8_LAS bf16x8*)(lds + PG8_SB(b, h) + boff + n * 2048 + k * 1024); } while (0)
; #define PG8_MMA(ai, bj, At, Bt) do { __builtin_amdgcn_s_setprio(1); _Pragma("unroll") for (int m = 0; m < 4; ++m) _Pragma("unroll") for (int n = 0; n < 2; ++n) _Pragma("unroll") for (int k = 0; k < 2; ++k) \
;         acc[ai][bj][m][n] = __builtin_amdgcn_mfma_f32_16x16x32_bf16(Bt[n][k], At[m][k], acc[ai][bj][m][n], 0, 0, 0); __builtin_amdgcn_s_setprio(0); } while (0)
; #define PG8_WAIT_V(n) asm volatile("s_waitcnt vmcnt(" #n ")" ::: "memory")
; #define PG8_WAIT_L(n) asm volatile("s_waitcnt lgkmcnt(" #n ")" ::: "memory")
; #define PG8_BAR __builtin_amdgcn_s_barrier()
; #define PG8_SCHED __builtin_amdgcn_sched_barrier(0)
; template <class Epi, class Sched, bool ALIGN_EPI = false, bool SP2 = false>
; __device__ __forceinline__ void gemm_phase(PG8_LAS unsigned char* lds, const Gemm g, const Sched& S, const Epi& E) {
;     ...
;         for (int t = 0; t < nt; t += 2) {
;     ...
;             PG8_WAIT_V(8); PG8_WAIT_L(0); PG8_BAR; PG8_MMA(1, 0, At, B0); PG8_MMA(1, 1, At, B1); PG8_BAR; PG8_SCHED;
;             PG8_LDB(B0, 1, 0); PG8_LDB(B1, 1, 1); PG8_SCHED; PG8_LDA(At, 1, 0); PG8_STAGE(PG8_SA(0, 1), a2 + hstep, voffA);
;             PG8_WAIT_V(8); PG8_WAIT_L(0); PG8_BAR; PG8_MMA(0, 0, At, B0); PG8_MMA(0, 1, At, B1); PG8_BAR; PG8_SCHED;
;             PG8_LDA(At, 1, 1); PG8_STAGE(PG8_SB(1, 0), b3, voffB); PG8_STAGE(PG8_SB(1, 1), b3 + hstep, voffB); PG8_STAGE(PG8_SA(1, 0), a3, voffA);
;             PG8_WAIT_V(8); PG8_WAIT_L(0); PG8_BAR; PG8_MMA(1, 0, At, B0); PG8_MMA(1, 1, At, B1); PG8_BAR; PG8_SCHED;
	s_setprio 0
	s_add_i32 s10, 16, 0x18000
	s_add_i32 s11, 16, 0x1c000
	v_add_u32_e32 v102, s10, v183
	v_add_u32_e32 v190, s11, v183
	ds_read_b128 v[90:93], v102
	ds_read_b128 v[94:97], v102 offset:1024
	ds_read_b128 v[98:101], v102 offset:2048
	ds_read_b128 v[102:105], v102 offset:3072
	ds_read_b128 v[158:161], v190
	ds_read_b128 v[176:179], v190 offset:1024
	ds_read_b128 v[186:189], v190 offset:2048
	ds_read_b128 v[190:193], v190 offset:3072
	s_add_u32 s48, s48, 0x40000
	s_addc_u32 s49, s49, 0
	s_mov_b32 m0, s9
	ds_read_b128 v[194:197], v185 offset:32768
	ds_read_b128 v[198:201], v185 offset:33792
	ds_read_b128 v[202:205], v185 offset:34816
	ds_read_b128 v[206:209], v185 offset:35840
	ds_read_b128 v[210:213], v185 offset:36864
	ds_read_b128 v[214:217], v185 offset:37888
	ds_read_b128 v[218:221], v185 offset:38912
	ds_read_b128 v[222:225], v185 offset:39936
	global_load_lds_dwordx4 v150, s[48:49]
	s_mov_b32 m0, s50
	s_nop 0
	global_load_lds_dwordx4 v148, s[48:49]
	s_waitcnt vmcnt(8)
	s_waitcnt lgkmcnt(0)
	s_setprio 1
	s_barrier
	v_mfma_f32_16x16x32_bf16 v[142:145], v[90:93], v[194:197], v[142:145]
	v_mfma_f32_16x16x32_bf16 v[138:141], v[98:101], v[194:197], v[138:141]
	v_mfma_f32_16x16x32_bf16 v[122:125], v[98:101], v[202:205], v[122:125]
	v_mfma_f32_16x16x32_bf16 v[126:129], v[90:93], v[202:205], v[126:129]
	v_mfma_f32_16x16x32_bf16 v[110:113], v[90:93], v[210:213], v[110:113]
	v_mfma_f32_16x16x32_bf16 v[106:109], v[98:101], v[210:213], v[106:109]
	v_mfma_f32_16x16x32_bf16 v[74:77], v[98:101], v[218:221], v[74:77]
	v_mfma_f32_16x16x32_bf16 v[78:81], v[90:93], v[218:221], v[78:81]
	v_mfma_f32_16x16x32_bf16 v[142:145], v[94:97], v[198:201], v[142:145]
	v_mfma_f32_16x16x32_bf16 v[138:141], v[102:105], v[198:201], v[138:141]
	v_mfma_f32_16x16x32_bf16 v[122:125], v[102:105], v[206:209], v[122:125]
	v_mfma_f32_16x16x32_bf16 v[126:129], v[94:97], v[206:209], v[126:129]
	v_mfma_f32_16x16x32_bf16 v[110:113], v[94:97], v[214:217], v[110:113]
	v_mfma_f32_16x16x32_bf16 v[106:109], v[102:105], v[214:217], v[106:109]
	v_mfma_f32_16x16x32_bf16 v[74:77], v[102:105], v[222:225], v[74:77]
	v_mfma_f32_16x16x32_bf16 v[78:81], v[94:97], v[222:225], v[78:81]
	v_mfma_f32_16x16x32_bf16 v[134:137], v[158:161], v[194:197], v[134:137]
	v_mfma_f32_16x16x32_bf16 v[130:133], v[186:189], v[194:197], v[130:133]
	v_mfma_f32_16x16x32_bf16 v[114:117], v[186:189], v[202:205], v[114:117]
	v_mfma_f32_16x16x32_bf16 v[118:121], v[158:161], v[202:205], v[118:121]
	v_mfma_f32_16x16x32_bf16 v[86:89], v[158:161], v[210:213], v[86:89]
	v_mfma_f32_16x16x32_bf16 v[82:85], v[186:189], v[210:213], v[82:85]
	v_mfma_f32_16x16x32_bf16 v[66:69], v[186:189], v[218:221], v[66:69]
	v_mfma_f32_16x16x32_bf16 v[70:73], v[158:161], v[218:221], v[70:73]
	v_mfma_f32_16x16x32_bf16 v[134:137], v[176:179], v[198:201], v[134:137]
	v_mfma_f32_16x16x32_bf16 v[130:133], v[190:193], v[198:201], v[130:133]
	v_mfma_f32_16x16x32_bf16 v[114:117], v[190:193], v[206:209], v[114:117]
	v_mfma_f32_16x16x32_bf16 v[118:121], v[176:179], v[206:209], v[118:121]
	v_mfma_f32_16x16x32_bf16 v[86:89], v[176:179], v[214:217], v[86:89]
	v_mfma_f32_16x16x32_bf16 v[82:85], v[190:193], v[214:217], v[82:85]
	v_mfma_f32_16x16x32_bf16 v[66:69], v[190:193], v[222:225], v[66:69]
	v_mfma_f32_16x16x32_bf16 v[70:73], v[176:179], v[222:225], v[70:73]
	s_barrier
	s_setprio 0
	s_add_i32 s10, s10, s6
	s_add_u32 s98, s46, s28
	s_addc_u32 s99, s47, s29
	s_mov_b32 m0, s10
	ds_read_b128 v[194:197], v185 offset:49152
	ds_read_b128 v[198:201], v185 offset:50176
	ds_read_b128 v[202:205], v185 offset:51200
	ds_read_b128 v[206:209], v185 offset:52224
	ds_read_b128 v[210:213], v185 offset:53248
	ds_read_b128 v[214:217], v185 offset:54272
	ds_read_b128 v[218:221], v185 offset:55296
	ds_read_b128 v[222:225], v185 offset:56320
	global_load_lds_dwordx4 v0, s[98:99]
	s_add_i32 m0, s10, 0x2000
	s_add_u32 s46, s46, 0x40080
	v_lshl_add_u64 v[180:181], v[226:227], 0, s[28:29]
	s_addc_u32 s47, s47, 0
	s_add_i32 s10, s11, s6
	global_load_lds_dwordx4 v[180:181], off
	s_mov_b32 m0, s10
	s_nop 0
	global_load_lds_dwordx4 v0, s[46:47]
	s_add_i32 m0, s10, 0x2000
	s_nop 0
	global_load_lds_dwordx4 v146, s[46:47]
	v_lshl_add_u64 v[180:181], v[238:239], 0, s[28:29]
	s_mov_b32 m0, s52
	s_nop 0
	global_load_lds_dwordx4 v[180:181], off
	v_lshl_add_u64 v[180:181], v[240:241], 0, s[28:29]
	s_mov_b32 m0, s53
	s_nop 0
	global_load_lds_dwordx4 v[180:181], off
	s_waitcnt vmcnt(8)
	s_waitcnt lgkmcnt(0)
	s_setprio 1
	s_barrier
	v_mfma_f32_16x16x32_bf16 v[62:65], v[90:93], v[194:197], v[62:65]
	v_mfma_f32_16x16x32_bf16 v[58:61], v[98:101], v[194:197], v[58:61]
	v_mfma_f32_16x16x32_bf16 v[42:45], v[98:101], v[202:205], v[42:45]
	v_mfma_f32_16x16x32_bf16 v[46:49], v[90:93], v[202:205], v[46:49]
	v_mfma_f32_16x16x32_bf16 v[30:33], v[90:93], v[210:213], v[30:33]
	v_mfma_f32_16x16x32_bf16 v[26:29], v[98:101], v[210:213], v[26:29]
	v_mfma_f32_16x16x32_bf16 v[10:13], v[98:101], v[218:221], v[10:13]
	v_mfma_f32_16x16x32_bf16 v[14:17], v[90:93], v[218:221], v[14:17]
	v_mfma_f32_16x16x32_bf16 v[62:65], v[94:97], v[198:201], v[62:65]
	v_mfma_f32_16x16x32_bf16 v[58:61], v[102:105], v[198:201], v[58:61]
	v_mfma_f32_16x16x32_bf16 v[42:45], v[102:105], v[206:209], v[42:45]
	v_mfma_f32_16x16x32_bf16 v[46:49], v[94:97], v[206:209], v[46:49]
	v_mfma_f32_16x16x32_bf16 v[30:33], v[94:97], v[214:217], v[30:33]
	v_mfma_f32_16x16x32_bf16 v[26:29], v[102:105], v[214:217], v[26:29]
	v_mfma_f32_16x16x32_bf16 v[10:13], v[102:105], v[222:225], v[10:13]
	v_mfma_f32_16x16x32_bf16 v[14:17], v[94:97], v[222:225], v[14:17]
	v_mfma_f32_16x16x32_bf16 v[54:57], v[158:161], v[194:197], v[54:57]
	v_mfma_f32_16x16x32_bf16 v[50:53], v[186:189], v[194:197], v[50:53]
	v_mfma_f32_16x16x32_bf16 v[34:37], v[186:189], v[202:205], v[34:37]
	v_mfma_f32_16x16x32_bf16 v[38:41], v[158:161], v[202:205], v[38:41]
	v_mfma_f32_16x16x32_bf16 v[22:25], v[158:161], v[210:213], v[22:25]
	v_mfma_f32_16x16x32_bf16 v[18:21], v[186:189], v[210:213], v[18:21]
	v_mfma_f32_16x16x32_bf16 v[2:5], v[186:189], v[218:221], v[2:5]
	v_mfma_f32_16x16x32_bf16 v[6:9], v[158:161], v[218:221], v[6:9]
	v_mfma_f32_16x16x32_bf16 v[54:57], v[176:179], v[198:201], v[54:57]
	v_mfma_f32_16x16x32_bf16 v[50:53], v[190:193], v[198:201], v[50:53]
	v_mfma_f32_16x16x32_bf16 v[34:37], v[190:193], v[206:209], v[34:37]
	v_mfma_f32_16x16x32_bf16 v[38:41], v[176:179], v[206:209], v[38:41]
	v_mfma_f32_16x16x32_bf16 v[22:25], v[176:179], v[214:217], v[22:25]
	v_mfma_f32_16x16x32_bf16 v[18:21], v[190:193], v[214:217], v[18:21]
	v_mfma_f32_16x16x32_bf16 v[2:5], v[190:193], v[222:225], v[2:5]
	v_mfma_f32_16x16x32_bf16 v[6:9], v[176:179], v[222:225], v[6:9]
	s_barrier
	s_setprio 0
	s_add_i32 s59, s59, 2
	s_add_u32 s57, s57, 0x100
	s_addc_u32 s58, s58, 0
	s_add_u32 s44, s44, 0x100
	s_addc_u32 s45, s45, 0
	s_cmp_gt_u32 s59, 13
	s_cbranch_scc0 .LBB0_162
	s_and_b64 vcc, exec, s[22:23]
	s_cbranch_vccz .LBB0_165
	s_barrier

; #define PG8_STAGE(bufoff, gbase, voff) do { _Pragma("unroll") for (int _i = 0; _i < 2; ++_i) \
;         __builtin_amdgcn_global_load_lds((const unsigned*)((const char*)(gbase) + (voff)[_i]), (PG8_LAS unsigned*)(lds + (bufoff) + ldsw + _i * 8192), 16, 0, 0); } while (0)
; #define PG8_LDA(dst, b, h) do { _Pragma("unroll") for (int m = 0; m < 4; ++m) _Pragma("unroll") for (int k = 0; k < 2; ++k) dst[m][k] = *(const PG8_LAS bf16x8*)(lds + PG8_SA(b, h) + aoff + m * 2048 + k * 1024); } while (0)
; #define PG8_LDB(dst, b, h) do { _Pragma("unroll") for (int n = 0; n < 2; ++n) _Pragma("unroll") for (int k = 0; k < 2; ++k) dst[n][k] = *(const PG8_LAS bf16x8*)(lds + PG8_SB(b, h) + boff + n * 2048 + k * 1024); } while (0)
; #define PG8_MMA(ai, bj, At, Bt) do { __builtin_amdgcn_s_setprio(1); _Pragma("unroll") for (int m = 0; m < 4; ++m) _Pragma("unroll") for (int n = 0; n < 2; ++n) _Pragma("unroll") for (int k = 0; k < 2; ++k) \
;         acc[ai][bj][m][n] = __builtin_amdgcn_mfma_f32_16x16x32_bf16(Bt[n][k], At[m][k], acc[ai][bj][m][n], 0, 0, 0); __builtin_amdgcn_s_setprio(0); } while (0)
; #define PG8_WAIT_V(n) asm volatile("s_waitcnt vmcnt(" #n ")" ::: "memory")
; #define PG8_WAIT_L(n) asm volatile("s_waitcnt lgkmcnt(" #n ")" ::: "memory")
; #define PG8_BAR __builtin_amdgcn_s_barrier()
; #define PG8_SCHED __builtin_amdgcn_sched_barrier(0)
; template <class Epi, class Sched, bool ALIGN_EPI = false, bool SP2 = false>
; __device__ __forceinline__ void gemm_phase(PG8_LAS unsigned char* lds, const Gemm g, const Sched& S, const Epi& E) {
;     ...
;             const bool last = (t == nt - 2);
;             const char* a1 = cA + (size_t)(t + 1) * kstep;
;             const char* a2 = last ? nA : cA + (size_t)(t + 2) * kstep; const char* b2 = last ? nB : cB + (size_t)(t + 2) * kstep;
;             const char* a3 = a2 + kstep; const char* b3 = b2 + kstep;
;             if (last && has_next) S.a_ready(nxt);
;             if constexpr (SP2) {
;             PG8_LDB(B0, 0, 0); PG8_LDB(B1, 0, 1); PG8_SCHED; PG8_LDA(At, 0, 0); PG8_STAGE(PG8_SA(1, 1), a1 + hstep, voffA);
;             PG8_WAIT_V(8); PG8_WAIT_L(0); PG8_BAR; PG8_MMA(0, 0, At, B0); PG8_MMA(0, 1, At, B1); PG8_BAR; PG8_SCHED;
;             PG8_LDA(At, 0, 1); PG8_STAGE(PG8_SB(0, 0), b2, voffB); PG8_STAGE(PG8_SB(0, 1), b2 + hstep, voffB); PG8_STAGE(PG8_SA(0, 0), a2, voffA);
.LBB0_243:
	s_add_u32 s10, s46, 0xfffc0080
	s_addc_u32 s11, s47, -1
	s_add_i32 s58, 16, 0x10000
	s_cmp_eq_u32 s57, 12
	s_cselect_b32 s51, s34, s11
	s_cselect_b32 s50, s35, s10
	s_cselect_b32 s49, s27, s56
	s_cselect_b32 s48, s41, s55
	s_add_i32 s10, 16, 0x14000
	v_add_u32_e32 v156, s58, v141
	v_add_u32_e32 v160, s10, v141
	ds_read_b128 v[144:147], v156
	ds_read_b128 v[148:151], v156 offset:1024
	ds_read_b128 v[152:155], v156 offset:2048
	ds_read_b128 v[156:159], v156 offset:3072
	ds_read_b128 v[176:179], v160
	ds_read_b128 v[180:183], v160 offset:1024
	ds_read_b128 v[184:187], v160 offset:2048
	ds_read_b128 v[188:191], v160 offset:3072
	s_add_i32 m0, s4, 0xc000
	ds_read_b128 v[192:195], v143
	ds_read_b128 v[196:199], v143 offset:1024
	ds_read_b128 v[200:203], v143 offset:2048
	ds_read_b128 v[204:207], v143 offset:3072
	ds_read_b128 v[208:211], v143 offset:4096
	ds_read_b128 v[212:215], v143 offset:5120
	ds_read_b128 v[216:219], v143 offset:6144
	ds_read_b128 v[220:223], v143 offset:7168
	global_load_lds_dwordx4 v138, s[46:47]
	s_add_i32 m0, s4, 0xe000
	s_nop 0
	global_load_lds_dwordx4 v136, s[46:47]
	s_waitcnt vmcnt(8)
	s_waitcnt lgkmcnt(0)
	s_setprio 1
	s_barrier
	v_mfma_f32_16x16x32_bf16 v[126:129], v[144:147], v[192:195], v[126:129]
	v_mfma_f32_16x16x32_bf16 v[122:125], v[152:155], v[192:195], v[122:125]
	v_mfma_f32_16x16x32_bf16 v[114:117], v[152:155], v[200:203], v[114:117]
	v_mfma_f32_16x16x32_bf16 v[118:121], v[144:147], v[200:203], v[118:121]
	v_mfma_f32_16x16x32_bf16 v[102:105], v[144:147], v[208:211], v[102:105]
	v_mfma_f32_16x16x32_bf16 v[98:101], v[152:155], v[208:211], v[98:101]
	v_mfma_f32_16x16x32_bf16 v[82:85], v[152:155], v[216:219], v[82:85]
	v_mfma_f32_16x16x32_bf16 v[86:89], v[144:147], v[216:219], v[86:89]
	v_mfma_f32_16x16x32_bf16 v[126:129], v[148:151], v[196:199], v[126:129]
	v_mfma_f32_16x16x32_bf16 v[122:125], v[156:159], v[196:199], v[122:125]
	v_mfma_f32_16x16x32_bf16 v[114:117], v[156:159], v[204:207], v[114:117]
	v_mfma_f32_16x16x32_bf16 v[118:121], v[148:151], v[204:207], v[118:121]
	v_mfma_f32_16x16x32_bf16 v[102:105], v[148:151], v[212:215], v[102:105]
	v_mfma_f32_16x16x32_bf16 v[98:101], v[156:159], v[212:215], v[98:101]
	v_mfma_f32_16x16x32_bf16 v[82:85], v[156:159], v[220:223], v[82:85]
	v_mfma_f32_16x16x32_bf16 v[86:89], v[148:151], v[220:223], v[86:89]
	v_mfma_f32_16x16x32_bf16 v[110:113], v[176:179], v[192:195], v[110:113]
	v_mfma_f32_16x16x32_bf16 v[106:109], v[184:187], v[192:195], v[106:109]
	v_mfma_f32_16x16x32_bf16 v[90:93], v[184:187], v[200:203], v[90:93]
	v_mfma_f32_16x16x32_bf16 v[94:97], v[176:179], v[200:203], v[94:97]
	v_mfma_f32_16x16x32_bf16 v[78:81], v[176:179], v[208:211], v[78:81]
	v_mfma_f32_16x16x32_bf16 v[74:77], v[184:187], v[208:211], v[74:77]
	v_mfma_f32_16x16x32_bf16 v[66:69], v[184:187], v[216:219], v[66:69]
	v_mfma_f32_16x16x32_bf16 v[70:73], v[176:179], v[216:219], v[70:73]
	v_mfma_f32_16x16x32_bf16 v[110:113], v[180:183], v[196:199], v[110:113]
	v_mfma_f32_16x16x32_bf16 v[106:109], v[188:191], v[196:199], v[106:109]
	v_mfma_f32_16x16x32_bf16 v[90:93], v[188:191], v[204:207], v[90:93]
	v_mfma_f32_16x16x32_bf16 v[94:97], v[180:183], v[204:207], v[94:97]
	v_mfma_f32_16x16x32_bf16 v[78:81], v[180:183], v[212:215], v[78:81]
	v_mfma_f32_16x16x32_bf16 v[74:77], v[188:191], v[212:215], v[74:77]
	v_mfma_f32_16x16x32_bf16 v[66:69], v[188:191], v[220:223], v[66:69]
	v_mfma_f32_16x16x32_bf16 v[70:73], v[180:183], v[220:223], v[70:73]
	s_barrier
	s_setprio 0
	s_add_i32 s11, s58, s3
	s_mov_b32 m0, s11
	ds_read_b128 v[192:195], v143 offset:16384
	ds_read_b128 v[196:199], v143 offset:17408
	ds_read_b128 v[200:203], v143 offset:18432
	ds_read_b128 v[204:207], v143 offset:19456
	ds_read_b128 v[208:211], v143 offset:20480
	ds_read_b128 v[212:215], v143 offset:21504
	ds_read_b128 v[216:219], v143 offset:22528
	ds_read_b128 v[220:223], v143 offset:23552
	global_load_lds_dwordx4 v0, s[48:49]
	s_add_i32 m0, s11, 0x2000
	s_add_u32 s58, s48, 0x40000
	v_lshl_add_u64 v[224:225], s[48:49], 0, v[130:131]
	s_addc_u32 s59, s49, 0
	s_add_i32 s10, s10, s3
	global_load_lds_dwordx4 v130, s[48:49]
	s_mov_b32 m0, s10
	v_lshl_add_u64 v[238:239], s[50:51], 0, v[132:133]
	s_nop 0
	global_load_lds_dwordx4 v0, s[58:59]
	s_add_i32 m0, s10, 0x2000
	s_nop 0
	global_load_lds_dwordx4 v130, s[58:59]
	v_lshl_add_u64 v[226:227], s[50:51], 0, v[134:135]
	s_mov_b32 m0, s4
	s_nop 0
	global_load_lds_dwordx4 v134, s[50:51]
	s_mov_b32 m0, s5
	s_nop 0
	global_load_lds_dwordx4 v132, s[50:51]
	s_waitcnt vmcnt(8)
	s_waitcnt lgkmcnt(0)
	s_setprio 1
	s_barrier
; #define PG8_STAGE(bufoff, gbase, voff) do { _Pragma("unroll") for (int _i = 0; _i < 2; ++_i) \
;         __builtin_amdgcn_global_load_lds((const unsigned*)((const char*)(gbase) + (voff)[_i]), (PG8_LAS unsigned*)(lds + (bufoff) + ldsw + _i * 8192), 16, 0, 0); } while (0)
; #define PG8_LDA(dst, b, h) do { _Pragma("unroll") for (int m = 0; m < 4; ++m) _Pragma("unroll") for (int k = 0; k < 2; ++k) dst[m][k] = *(const PG8_LAS bf16x8*)(lds + PG8_SA(b, h) + aoff + m * 2048 + k * 1024); } while (0)
; #define PG8_LDB(dst, b, h) do { _Pragma("unroll") for (int n = 0; n < 2; ++n) _Pragma("unroll") for (int k = 0; k < 2; ++k) dst[n][k] = *(const PG8_LAS bf16x8*)(lds + PG8_SB(b, h) + boff + n * 2048 + k * 1024); } while (0)
; #define PG8_MMA(ai, bj, At, Bt) do { __builtin_amdgcn_s_setprio(1); _Pragma("unroll") for (int m = 0; m < 4; ++m) _Pragma("unroll") for (int n = 0; n < 2; ++n) _Pragma("unroll") for (int k = 0; k < 2; ++k) \
;         acc[ai][bj][m][n] = __builtin_amdgcn_mfma_f32_16x16x32_bf16(Bt[n][k], At[m][k], acc[ai][bj][m][n], 0, 0, 0); __builtin_amdgcn_s_setprio(0); } while (0)
; #define PG8_WAIT_V(n) asm volatile("s_waitcnt vmcnt(" #n ")" ::: "memory")
; #define PG8_WAIT_L(n) asm volatile("s_waitcnt lgkmcnt(" #n ")" ::: "memory")
; #define PG8_BAR __builtin_amdgcn_s_barrier()
; #define PG8_SCHED __builtin_amdgcn_sched_barrier(0)
; template <class Epi, class Sched, bool ALIGN_EPI = false, bool SP2 = false>
; __device__ __forceinline__ void gemm_phase(PG8_LAS unsigned char* lds, const Gemm g, const Sched& S, const Epi& E) {
;     ...
;             PG8_WAIT_V(8); PG8_WAIT_L(0); PG8_BAR; PG8_MMA(1, 0, At, B0); PG8_MMA(1, 1, At, B1); PG8_BAR; PG8_SCHED;
;             PG8_LDB(B0, 1, 0); PG8_LDB(B1, 1, 1); PG8_SCHED; PG8_LDA(At, 1, 0); PG8_STAGE(PG8_SA(0, 1), a2 + hstep, voffA);
;             PG8_WAIT_V(8); PG8_WAIT_L(0); PG8_BAR; PG8_MMA(0, 0, At, B0); PG8_MMA(0, 1, At, B1); PG8_BAR; PG8_SCHED;
	v_mfma_f32_16x16x32_bf16 v[62:65], v[144:147], v[192:195], v[62:65]
	v_mfma_f32_16x16x32_bf16 v[58:61], v[152:155], v[192:195], v[58:61]
	v_mfma_f32_16x16x32_bf16 v[50:53], v[152:155], v[200:203], v[50:53]
	v_mfma_f32_16x16x32_bf16 v[54:57], v[144:147], v[200:203], v[54:57]
	v_mfma_f32_16x16x32_bf16 v[38:41], v[144:147], v[208:211], v[38:41]
	v_mfma_f32_16x16x32_bf16 v[34:37], v[152:155], v[208:211], v[34:37]
	v_mfma_f32_16x16x32_bf16 v[18:21], v[152:155], v[216:219], v[18:21]
	v_mfma_f32_16x16x32_bf16 v[22:25], v[144:147], v[216:219], v[22:25]
	v_mfma_f32_16x16x32_bf16 v[62:65], v[148:151], v[196:199], v[62:65]
	v_mfma_f32_16x16x32_bf16 v[58:61], v[156:159], v[196:199], v[58:61]
	v_mfma_f32_16x16x32_bf16 v[50:53], v[156:159], v[204:207], v[50:53]
	v_mfma_f32_16x16x32_bf16 v[54:57], v[148:151], v[204:207], v[54:57]
	v_mfma_f32_16x16x32_bf16 v[38:41], v[148:151], v[212:215], v[38:41]
	v_mfma_f32_16x16x32_bf16 v[34:37], v[156:159], v[212:215], v[34:37]
	v_mfma_f32_16x16x32_bf16 v[18:21], v[156:159], v[220:223], v[18:21]
	v_mfma_f32_16x16x32_bf16 v[22:25], v[148:151], v[220:223], v[22:25]
	v_mfma_f32_16x16x32_bf16 v[46:49], v[176:179], v[192:195], v[46:49]
	v_mfma_f32_16x16x32_bf16 v[42:45], v[184:187], v[192:195], v[42:45]
	v_mfma_f32_16x16x32_bf16 v[26:29], v[184:187], v[200:203], v[26:29]
	v_mfma_f32_16x16x32_bf16 v[30:33], v[176:179], v[200:203], v[30:33]
	v_mfma_f32_16x16x32_bf16 v[14:17], v[176:179], v[208:211], v[14:17]
	v_mfma_f32_16x16x32_bf16 v[10:13], v[184:187], v[208:211], v[10:13]
	v_mfma_f32_16x16x32_bf16 v[2:5], v[184:187], v[216:219], v[2:5]
	v_mfma_f32_16x16x32_bf16 v[6:9], v[176:179], v[216:219], v[6:9]
	v_mfma_f32_16x16x32_bf16 v[46:49], v[180:183], v[196:199], v[46:49]
	v_mfma_f32_16x16x32_bf16 v[42:45], v[188:191], v[196:199], v[42:45]
	v_mfma_f32_16x16x32_bf16 v[26:29], v[188:191], v[204:207], v[26:29]
	v_mfma_f32_16x16x32_bf16 v[30:33], v[180:183], v[204:207], v[30:33]
	v_mfma_f32_16x16x32_bf16 v[14:17], v[180:183], v[212:215], v[14:17]
	v_mfma_f32_16x16x32_bf16 v[10:13], v[188:191], v[212:215], v[10:13]
	v_mfma_f32_16x16x32_bf16 v[2:5], v[188:191], v[220:223], v[2:5]
	v_mfma_f32_16x16x32_bf16 v[6:9], v[180:183], v[220:223], v[6:9]
	s_barrier
	s_setprio 0
	s_add_i32 s10, 16, 0x18000
	s_add_i32 s11, 16, 0x1c000
	v_add_u32_e32 v156, s10, v141
	v_add_u32_e32 v188, s11, v141
	ds_read_b128 v[144:147], v156
	ds_read_b128 v[148:151], v156 offset:1024
	ds_read_b128 v[152:155], v156 offset:2048
	ds_read_b128 v[156:159], v156 offset:3072
	ds_read_b128 v[176:179], v188
	ds_read_b128 v[180:183], v188 offset:1024
	ds_read_b128 v[184:187], v188 offset:2048
	ds_read_b128 v[188:191], v188 offset:3072
	s_add_u32 s50, s50, 0x40000
	s_addc_u32 s51, s51, 0
	s_mov_b32 m0, s6
	ds_read_b128 v[192:195], v143 offset:32768
	ds_read_b128 v[196:199], v143 offset:33792
	ds_read_b128 v[200:203], v143 offset:34816
	ds_read_b128 v[204:207], v143 offset:35840
	ds_read_b128 v[208:211], v143 offset:36864
	ds_read_b128 v[212:215], v143 offset:37888
	ds_read_b128 v[216:219], v143 offset:38912
	ds_read_b128 v[220:223], v143 offset:39936
	global_load_lds_dwordx4 v134, s[50:51]
	s_mov_b32 m0, s7
	s_nop 0
	global_load_lds_dwordx4 v132, s[50:51]
	s_waitcnt vmcnt(8)
	s_waitcnt lgkmcnt(0)
	s_setprio 1
	s_barrier
	v_mfma_f32_16x16x32_bf16 v[126:129], v[144:147], v[192:195], v[126:129]
	v_mfma_f32_16x16x32_bf16 v[122:125], v[152:155], v[192:195], v[122:125]
	v_mfma_f32_16x16x32_bf16 v[114:117], v[152:155], v[200:203], v[114:117]
	v_mfma_f32_16x16x32_bf16 v[118:121], v[144:147], v[200:203], v[118:121]
	v_mfma_f32_16x16x32_bf16 v[102:105], v[144:147], v[208:211], v[102:105]
	v_mfma_f32_16x16x32_bf16 v[98:101], v[152:155], v[208:211], v[98:101]
	v_mfma_f32_16x16x32_bf16 v[82:85], v[152:155], v[216:219], v[82:85]
	v_mfma_f32_16x16x32_bf16 v[86:89], v[144:147], v[216:219], v[86:89]
	v_mfma_f32_16x16x32_bf16 v[126:129], v[148:151], v[196:199], v[126:129]
	v_mfma_f32_16x16x32_bf16 v[122:125], v[156:159], v[196:199], v[122:125]
	v_mfma_f32_16x16x32_bf16 v[114:117], v[156:159], v[204:207], v[114:117]
	v_mfma_f32_16x16x32_bf16 v[118:121], v[148:151], v[204:207], v[118:121]
	v_mfma_f32_16x16x32_bf16 v[102:105], v[148:151], v[212:215], v[102:105]
	v_mfma_f32_16x16x32_bf16 v[98:101], v[156:159], v[212:215], v[98:101]
	v_mfma_f32_16x16x32_bf16 v[82:85], v[156:159], v[220:223], v[82:85]
	v_mfma_f32_16x16x32_bf16 v[86:89], v[148:151], v[220:223], v[86:89]
	v_mfma_f32_16x16x32_bf16 v[110:113], v[176:179], v[192:195], v[110:113]
	v_mfma_f32_16x16x32_bf16 v[106:109], v[184:187], v[192:195], v[106:109]
	v_mfma_f32_16x16x32_bf16 v[90:93], v[184:187], v[200:203], v[90:93]
	v_mfma_f32_16x16x32_bf16 v[94:97], v[176:179], v[200:203], v[94:97]
	v_mfma_f32_16x16x32_bf16 v[78:81], v[176:179], v[208:211], v[78:81]
	v_mfma_f32_16x16x32_bf16 v[74:77], v[184:187], v[208:211], v[74:77]
	v_mfma_f32_16x16x32_bf16 v[66:69], v[184:187], v[216:219], v[66:69]
	v_mfma_f32_16x16x32_bf16 v[70:73], v[176:179], v[216:219], v[70:73]
	v_mfma_f32_16x16x32_bf16 v[110:113], v[180:183], v[196:199], v[110:113]
	v_mfma_f32_16x16x32_bf16 v[106:109], v[188:191], v[196:199], v[106:109]
	v_mfma_f32_16x16x32_bf16 v[90:93], v[188:191], v[204:207], v[90:93]
	v_mfma_f32_16x16x32_bf16 v[94:97], v[180:183], v[204:207], v[94:97]
	v_mfma_f32_16x16x32_bf16 v[78:81], v[180:183], v[212:215], v[78:81]
	v_mfma_f32_16x16x32_bf16 v[74:77], v[188:191], v[212:215], v[74:77]
	v_mfma_f32_16x16x32_bf16 v[66:69], v[188:191], v[220:223], v[66:69]
	v_mfma_f32_16x16x32_bf16 v[70:73], v[180:183], v[220:223], v[70:73]
	s_barrier
; #define PG8_STAGE(bufoff, gbase, voff) do { _Pragma("unroll") for (int _i = 0; _i < 2; ++_i) \
;         __builtin_amdgcn_global_load_lds((const unsigned*)((const char*)(gbase) + (voff)[_i]), (PG8_LAS unsigned*)(lds + (bufoff) + ldsw + _i * 8192), 16, 0, 0); } while (0)
; #define PG8_LDA(dst, b, h) do { _Pragma("unroll") for (int m = 0; m < 4; ++m) _Pragma("unroll") for (int k = 0; k < 2; ++k) dst[m][k] = *(const PG8_LAS bf16x8*)(lds + PG8_SA(b, h) + aoff + m * 2048 + k * 1024); } while (0)
; #define PG8_MMA(ai, bj, At, Bt) do { __builtin_amdgcn_s_setprio(1); _Pragma("unroll") for (int m = 0; m < 4; ++m) _Pragma("unroll") for (int n = 0; n < 2; ++n) _Pragma("unroll") for (int k = 0; k < 2; ++k) \
;         acc[ai][bj][m][n] = __builtin_amdgcn_mfma_f32_16x16x32_bf16(Bt[n][k], At[m][k], acc[ai][bj][m][n], 0, 0, 0); __builtin_amdgcn_s_setprio(0); } while (0)
; #define PG8_WAIT_V(n) asm volatile("s_waitcnt vmcnt(" #n ")" ::: "memory")
; #define PG8_WAIT_L(n) asm volatile("s_waitcnt lgkmcnt(" #n ")" ::: "memory")
; #define PG8_BAR __builtin_amdgcn_s_barrier()
; #define PG8_SCHED __builtin_amdgcn_sched_barrier(0)
; template <class Epi, class Sched, bool ALIGN_EPI = false, bool SP2 = false>
; __device__ __forceinline__ void gemm_phase(PG8_LAS unsigned char* lds, const Gemm g, const Sched& S, const Epi& E) {
;     ...
;         for (int t = 0; t < nt; t += 2) {
;     ...
;             PG8_LDA(At, 1, 1); PG8_STAGE(PG8_SB(1, 0), b3, voffB); PG8_STAGE(PG8_SB(1, 1), b3 + hstep, voffB); PG8_STAGE(PG8_SA(1, 0), a3, voffA);
;             PG8_WAIT_V(8); PG8_WAIT_L(0); PG8_BAR; PG8_MMA(1, 0, At, B0); PG8_MMA(1, 1, At, B1); PG8_BAR; PG8_SCHED;
	s_setprio 0
	s_add_i32 s10, s10, s3
	s_add_u32 s98, s48, s28
	s_addc_u32 s99, s49, s29
	s_mov_b32 m0, s10
	ds_read_b128 v[192:195], v143 offset:49152
	ds_read_b128 v[196:199], v143 offset:50176
	ds_read_b128 v[200:203], v143 offset:51200
	ds_read_b128 v[204:207], v143 offset:52224
	ds_read_b128 v[208:211], v143 offset:53248
	ds_read_b128 v[212:215], v143 offset:54272
	ds_read_b128 v[216:219], v143 offset:55296
	ds_read_b128 v[220:223], v143 offset:56320
	global_load_lds_dwordx4 v0, s[98:99]
	s_add_i32 m0, s10, 0x2000
	s_add_u32 s48, s48, 0x40080
	v_lshl_add_u64 v[160:161], v[224:225], 0, s[28:29]
	s_addc_u32 s49, s49, 0
	s_add_i32 s10, s11, s3
	global_load_lds_dwordx4 v[160:161], off
	s_mov_b32 m0, s10
	s_nop 0
	global_load_lds_dwordx4 v0, s[48:49]
	s_add_i32 m0, s10, 0x2000
	s_nop 0
	global_load_lds_dwordx4 v130, s[48:49]
	v_lshl_add_u64 v[160:161], v[226:227], 0, s[28:29]
	s_mov_b32 m0, s8
	s_nop 0
	global_load_lds_dwordx4 v[160:161], off
	v_lshl_add_u64 v[160:161], v[238:239], 0, s[28:29]
	s_mov_b32 m0, s9
	s_nop 0
	global_load_lds_dwordx4 v[160:161], off
	s_waitcnt vmcnt(8)
	s_waitcnt lgkmcnt(0)
	s_setprio 1
	s_barrier
	v_mfma_f32_16x16x32_bf16 v[62:65], v[144:147], v[192:195], v[62:65]
	v_mfma_f32_16x16x32_bf16 v[58:61], v[152:155], v[192:195], v[58:61]
	v_mfma_f32_16x16x32_bf16 v[50:53], v[152:155], v[200:203], v[50:53]
	v_mfma_f32_16x16x32_bf16 v[54:57], v[144:147], v[200:203], v[54:57]
	v_mfma_f32_16x16x32_bf16 v[38:41], v[144:147], v[208:211], v[38:41]
	v_mfma_f32_16x16x32_bf16 v[34:37], v[152:155], v[208:211], v[34:37]
	v_mfma_f32_16x16x32_bf16 v[18:21], v[152:155], v[216:219], v[18:21]
	v_mfma_f32_16x16x32_bf16 v[22:25], v[144:147], v[216:219], v[22:25]
	v_mfma_f32_16x16x32_bf16 v[62:65], v[148:151], v[196:199], v[62:65]
	v_mfma_f32_16x16x32_bf16 v[58:61], v[156:159], v[196:199], v[58:61]
	v_mfma_f32_16x16x32_bf16 v[50:53], v[156:159], v[204:207], v[50:53]
	v_mfma_f32_16x16x32_bf16 v[54:57], v[148:151], v[204:207], v[54:57]
	v_mfma_f32_16x16x32_bf16 v[38:41], v[148:151], v[212:215], v[38:41]
	v_mfma_f32_16x16x32_bf16 v[34:37], v[156:159], v[212:215], v[34:37]
	v_mfma_f32_16x16x32_bf16 v[18:21], v[156:159], v[220:223], v[18:21]
	v_mfma_f32_16x16x32_bf16 v[22:25], v[148:151], v[220:223], v[22:25]
	v_mfma_f32_16x16x32_bf16 v[46:49], v[176:179], v[192:195], v[46:49]
	v_mfma_f32_16x16x32_bf16 v[42:45], v[184:187], v[192:195], v[42:45]
	v_mfma_f32_16x16x32_bf16 v[26:29], v[184:187], v[200:203], v[26:29]
	v_mfma_f32_16x16x32_bf16 v[30:33], v[176:179], v[200:203], v[30:33]
	v_mfma_f32_16x16x32_bf16 v[14:17], v[176:179], v[208:211], v[14:17]
	v_mfma_f32_16x16x32_bf16 v[10:13], v[184:187], v[208:211], v[10:13]
	v_mfma_f32_16x16x32_bf16 v[2:5], v[184:187], v[216:219], v[2:5]
	v_mfma_f32_16x16x32_bf16 v[6:9], v[176:179], v[216:219], v[6:9]
	v_mfma_f32_16x16x32_bf16 v[46:49], v[180:183], v[196:199], v[46:49]
	v_mfma_f32_16x16x32_bf16 v[42:45], v[188:191], v[196:199], v[42:45]
	v_mfma_f32_16x16x32_bf16 v[26:29], v[188:191], v[204:207], v[26:29]
	v_mfma_f32_16x16x32_bf16 v[30:33], v[180:183], v[204:207], v[30:33]
	v_mfma_f32_16x16x32_bf16 v[14:17], v[180:183], v[212:215], v[14:17]
	v_mfma_f32_16x16x32_bf16 v[10:13], v[188:191], v[212:215], v[10:13]
	v_mfma_f32_16x16x32_bf16 v[2:5], v[188:191], v[220:223], v[2:5]
	v_mfma_f32_16x16x32_bf16 v[6:9], v[180:183], v[220:223], v[6:9]
	s_barrier
	s_setprio 0
	s_add_i32 s57, s57, 2
	s_add_u32 s55, s55, 0x100
	s_addc_u32 s56, s56, 0
	s_add_u32 s46, s46, 0x100
	s_addc_u32 s47, s47, 0
	s_cmp_gt_u32 s57, 13
	s_cbranch_scc0 .LBB0_243
	s_and_b64 vcc, exec, s[24:25]
	s_cbranch_vccz .LBB0_246
	s_barrier

; #define PG8_STAGE(bufoff, gbase, voff) do { _Pragma("unroll") for (int _i = 0; _i < 2; ++_i) \
;         __builtin_amdgcn_global_load_lds((const unsigned*)((const char*)(gbase) + (voff)[_i]), (PG8_LAS unsigned*)(lds + (bufoff) + ldsw + _i * 8192), 16, 0, 0); } while (0)
; #define PG8_LDA(dst, b, h) do { _Pragma("unroll") for (int m = 0; m < 4; ++m) _Pragma("unroll") for (int k = 0; k < 2; ++k) dst[m][k] = *(const PG8_LAS bf16x8*)(lds + PG8_SA(b, h) + aoff + m * 2048 + k * 1024); } while (0)
; #define PG8_LDB(dst, b, h) do { _Pragma("unroll") for (int n = 0; n < 2; ++n) _Pragma("unroll") for (int k = 0; k < 2; ++k) dst[n][k] = *(const PG8_LAS bf16x8*)(lds + PG8_SB(b, h) + boff + n * 2048 + k * 1024); } while (0)
; #define PG8_MMA(ai, bj, At, Bt) do { __builtin_amdgcn_s_setprio(1); _Pragma("unroll") for (int m = 0; m < 4; ++m) _Pragma("unroll") for (int n = 0; n < 2; ++n) _Pragma("unroll") for (int k = 0; k < 2; ++k) \
;         acc[ai][bj][m][n] = __builtin_amdgcn_mfma_f32_16x16x32_bf16(Bt[n][k], At[m][k], acc[ai][bj][m][n], 0, 0, 0); __builtin_amdgcn_s_setprio(0); } while (0)
; #define PG8_WAIT_V(n) asm volatile("s_waitcnt vmcnt(" #n ")" ::: "memory")
; #define PG8_WAIT_L(n) asm volatile("s_waitcnt lgkmcnt(" #n ")" ::: "memory")
; template <class Epi, class Sched, bool ALIGN_EPI = false, bool SP2 = false>
; __device__ __forceinline__ void gemm_phase(PG8_LAS unsigned char* lds, const Gemm g, const Sched& S, const Epi& E) {
;     ...
;             const bool last = (t == nt - 2);
;             const char* a1 = cA + (size_t)(t + 1) * kstep;
;             const char* a2 = last ? nA : cA + (size_t)(t + 2) * kstep; const char* b2 = last ? nB : cB + (size_t)(t + 2) * kstep;
;             const char* a3 = a2 + kstep; const char* b3 = b2 + kstep;
;             if (last && has_next) S.a_ready(nxt);
;             if constexpr (SP2) {
;             PG8_LDB(B0, 0, 0); PG8_LDB(B1, 0, 1); PG8_SCHED; PG8_LDA(At, 0, 0); PG8_STAGE(PG8_SA(1, 1), a1 + hstep, voffA);
;             PG8_WAIT_V(8); PG8_WAIT_L(0); PG8_BAR; PG8_MMA(0, 0, At, B0); PG8_MMA(0, 1, At, B1); PG8_BAR; PG8_SCHED;
;             PG8_LDA(At, 0, 1); PG8_STAGE(PG8_SB(0, 0), b2, voffB); PG8_STAGE(PG8_SB(0, 1), b2 + hstep, voffB); PG8_STAGE(PG8_SA(0, 0), a2, voffA);
;             PG8_WAIT_V(8); PG8_WAIT_L(0); PG8_BAR; PG8_MMA(1, 0, At, B0); PG8_MMA(1, 1, At, B1); PG8_BAR; PG8_SCHED;
.LBB0_915:
	s_add_u32 s10, s42, 0xfffc0080
	s_addc_u32 s11, s43, -1
	s_add_i32 s35, 16, 0x10000
	s_cmp_eq_u32 s34, 12
	s_cselect_b32 s73, s0, s11
	s_cselect_b32 s72, s8, s10
	s_cselect_b32 s69, s9, s27
	s_cselect_b32 s68, s23, s25
	s_add_i32 s45, 16, 0x14000
	v_add_u32_e32 v78, s35, v197
	v_add_u32_e32 v94, s45, v197
	ds_read_b128 v[58:61], v78
	ds_read_b128 v[62:65], v78 offset:1024
	ds_read_b128 v[74:77], v78 offset:2048
	ds_read_b128 v[78:81], v78 offset:3072
	ds_read_b128 v[82:85], v94
	ds_read_b128 v[86:89], v94 offset:1024
	ds_read_b128 v[90:93], v94 offset:2048
	ds_read_b128 v[94:97], v94 offset:3072
	s_add_i32 m0, s77, 0xc000
	ds_read_b128 v[186:189], v199
	ds_read_b128 v[190:193], v199 offset:1024
	ds_read_b128 v[200:203], v199 offset:2048
	ds_read_b128 v[204:207], v199 offset:3072
	ds_read_b128 v[208:211], v199 offset:4096
	ds_read_b128 v[212:215], v199 offset:5120
	ds_read_b128 v[216:219], v199 offset:6144
	ds_read_b128 v[220:223], v199 offset:7168
	global_load_lds_dwordx4 v184, s[42:43]
	s_add_i32 m0, s77, 0xe000
	s_nop 0
	global_load_lds_dwordx4 v182, s[42:43]
	s_waitcnt vmcnt(8)
	s_waitcnt lgkmcnt(0)
	s_setprio 1
	s_barrier
	v_mfma_f32_16x16x32_bf16 v[158:161], v[58:61], v[186:189], v[158:161]
	v_mfma_f32_16x16x32_bf16 v[154:157], v[74:77], v[186:189], v[154:157]
	v_mfma_f32_16x16x32_bf16 v[138:141], v[74:77], v[200:203], v[138:141]
	v_mfma_f32_16x16x32_bf16 v[142:145], v[58:61], v[200:203], v[142:145]
	v_mfma_f32_16x16x32_bf16 v[126:129], v[58:61], v[208:211], v[126:129]
	v_mfma_f32_16x16x32_bf16 v[122:125], v[74:77], v[208:211], v[122:125]
	v_mfma_f32_16x16x32_bf16 v[106:109], v[74:77], v[216:219], v[106:109]
	v_mfma_f32_16x16x32_bf16 v[110:113], v[58:61], v[216:219], v[110:113]
	v_mfma_f32_16x16x32_bf16 v[158:161], v[62:65], v[190:193], v[158:161]
	v_mfma_f32_16x16x32_bf16 v[154:157], v[78:81], v[190:193], v[154:157]
	v_mfma_f32_16x16x32_bf16 v[138:141], v[78:81], v[204:207], v[138:141]
	v_mfma_f32_16x16x32_bf16 v[142:145], v[62:65], v[204:207], v[142:145]
	v_mfma_f32_16x16x32_bf16 v[126:129], v[62:65], v[212:215], v[126:129]
	v_mfma_f32_16x16x32_bf16 v[122:125], v[78:81], v[212:215], v[122:125]
	v_mfma_f32_16x16x32_bf16 v[106:109], v[78:81], v[220:223], v[106:109]
	v_mfma_f32_16x16x32_bf16 v[110:113], v[62:65], v[220:223], v[110:113]
	v_mfma_f32_16x16x32_bf16 v[150:153], v[82:85], v[186:189], v[150:153]
	v_mfma_f32_16x16x32_bf16 v[146:149], v[90:93], v[186:189], v[146:149]
	v_mfma_f32_16x16x32_bf16 v[130:133], v[90:93], v[200:203], v[130:133]
	v_mfma_f32_16x16x32_bf16 v[134:137], v[82:85], v[200:203], v[134:137]
	v_mfma_f32_16x16x32_bf16 v[118:121], v[82:85], v[208:211], v[118:121]
	v_mfma_f32_16x16x32_bf16 v[114:117], v[90:93], v[208:211], v[114:117]
	v_mfma_f32_16x16x32_bf16 v[98:101], v[90:93], v[216:219], v[98:101]
	v_mfma_f32_16x16x32_bf16 v[102:105], v[82:85], v[216:219], v[102:105]
	v_mfma_f32_16x16x32_bf16 v[150:153], v[86:89], v[190:193], v[150:153]
	v_mfma_f32_16x16x32_bf16 v[146:149], v[94:97], v[190:193], v[146:149]
	v_mfma_f32_16x16x32_bf16 v[130:133], v[94:97], v[204:207], v[130:133]
	v_mfma_f32_16x16x32_bf16 v[134:137], v[86:89], v[204:207], v[134:137]
	v_mfma_f32_16x16x32_bf16 v[118:121], v[86:89], v[212:215], v[118:121]
	v_mfma_f32_16x16x32_bf16 v[114:117], v[94:97], v[212:215], v[114:117]
	v_mfma_f32_16x16x32_bf16 v[98:101], v[94:97], v[220:223], v[98:101]
	v_mfma_f32_16x16x32_bf16 v[102:105], v[86:89], v[220:223], v[102:105]
	s_barrier
	s_setprio 0
	s_add_i32 s10, s35, s76
	s_mov_b32 m0, s10
	ds_read_b128 v[186:189], v199 offset:16384
	ds_read_b128 v[190:193], v199 offset:17408
	ds_read_b128 v[200:203], v199 offset:18432
	ds_read_b128 v[204:207], v199 offset:19456
	ds_read_b128 v[208:211], v199 offset:20480
	ds_read_b128 v[212:215], v199 offset:21504
	ds_read_b128 v[216:219], v199 offset:22528
	ds_read_b128 v[220:223], v199 offset:23552
	global_load_lds_dwordx4 v0, s[68:69]
	s_add_i32 m0, s10, 0x2000
	s_add_u32 s10, s68, 0x40000
	s_addc_u32 s11, s69, 0
	s_add_i32 s35, s45, s76
	global_load_lds_dwordx4 v180, s[68:69]
	s_mov_b32 m0, s35
	s_nop 0
	global_load_lds_dwordx4 v0, s[10:11]
	s_add_i32 m0, s35, 0x2000
	s_nop 0
	global_load_lds_dwordx4 v180, s[10:11]
	s_mov_b32 m0, s77
	s_nop 0
	global_load_lds_dwordx4 v176, s[72:73]
	s_mov_b32 m0, s2
	s_nop 0
	global_load_lds_dwordx4 v178, s[72:73]
	s_waitcnt vmcnt(8)
	s_waitcnt lgkmcnt(0)
	s_setprio 1
	s_barrier
	v_mfma_f32_16x16x32_bf16 v[70:73], v[58:61], v[186:189], v[70:73]
	v_mfma_f32_16x16x32_bf16 v[66:69], v[74:77], v[186:189], v[66:69]
	v_mfma_f32_16x16x32_bf16 v[42:45], v[74:77], v[200:203], v[42:45]
	v_mfma_f32_16x16x32_bf16 v[46:49], v[58:61], v[200:203], v[46:49]
	v_mfma_f32_16x16x32_bf16 v[30:33], v[58:61], v[208:211], v[30:33]
	v_mfma_f32_16x16x32_bf16 v[26:29], v[74:77], v[208:211], v[26:29]
	v_mfma_f32_16x16x32_bf16 v[10:13], v[74:77], v[216:219], v[10:13]
	v_mfma_f32_16x16x32_bf16 v[14:17], v[58:61], v[216:219], v[14:17]
	v_mfma_f32_16x16x32_bf16 v[70:73], v[62:65], v[190:193], v[70:73]
	v_mfma_f32_16x16x32_bf16 v[66:69], v[78:81], v[190:193], v[66:69]
	v_mfma_f32_16x16x32_bf16 v[42:45], v[78:81], v[204:207], v[42:45]
	v_mfma_f32_16x16x32_bf16 v[46:49], v[62:65], v[204:207], v[46:49]
	v_mfma_f32_16x16x32_bf16 v[30:33], v[62:65], v[212:215], v[30:33]
	v_mfma_f32_16x16x32_bf16 v[26:29], v[78:81], v[212:215], v[26:29]
	v_mfma_f32_16x16x32_bf16 v[10:13], v[78:81], v[220:223], v[10:13]
	v_mfma_f32_16x16x32_bf16 v[14:17], v[62:65], v[220:223], v[14:17]
	v_mfma_f32_16x16x32_bf16 v[54:57], v[82:85], v[186:189], v[54:57]
	v_mfma_f32_16x16x32_bf16 v[50:53], v[90:93], v[186:189], v[50:53]
	v_mfma_f32_16x16x32_bf16 v[34:37], v[90:93], v[200:203], v[34:37]
	v_mfma_f32_16x16x32_bf16 v[38:41], v[82:85], v[200:203], v[38:41]
	v_mfma_f32_16x16x32_bf16 v[22:25], v[82:85], v[208:211], v[22:25]
	v_mfma_f32_16x16x32_bf16 v[18:21], v[90:93], v[208:211], v[18:21]
	v_mfma_f32_16x16x32_bf16 v[2:5], v[90:93], v[216:219], v[2:5]
	v_mfma_f32_16x16x32_bf16 v[6:9], v[82:85], v[216:219], v[6:9]
	v_mfma_f32_16x16x32_bf16 v[54:57], v[86:89], v[190:193], v[54:57]
	v_mfma_f32_16x16x32_bf16 v[50:53], v[94:97], v[190:193], v[50:53]
	v_mfma_f32_16x16x32_bf16 v[34:37], v[94:97], v[204:207], v[34:37]
	v_mfma_f32_16x16x32_bf16 v[38:41], v[86:89], v[204:207], v[38:41]
	v_mfma_f32_16x16x32_bf16 v[22:25], v[86:89], v[212:215], v[22:25]
	v_mfma_f32_16x16x32_bf16 v[18:21], v[94:97], v[212:215], v[18:21]
	v_mfma_f32_16x16x32_bf16 v[2:5], v[94:97], v[220:223], v[2:5]
	v_mfma_f32_16x16x32_bf16 v[6:9], v[86:89], v[220:223], v[6:9]
	s_barrier
; #define PG8_STAGE(bufoff, gbase, voff) do { _Pragma("unroll") for (int _i = 0; _i < 2; ++_i) \
;         __builtin_amdgcn_global_load_lds((const unsigned*)((const char*)(gbase) + (voff)[_i]), (PG8_LAS unsigned*)(lds + (bufoff) + ldsw + _i * 8192), 16, 0, 0); } while (0)
; #define PG8_LDA(dst, b, h) do { _Pragma("unroll") for (int m = 0; m < 4; ++m) _Pragma("unroll") for (int k = 0; k < 2; ++k) dst[m][k] = *(const PG8_LAS bf16x8*)(lds + PG8_SA(b, h) + aoff + m * 2048 + k * 1024); } while (0)
; #define PG8_LDB(dst, b, h) do { _Pragma("unroll") for (int n = 0; n < 2; ++n) _Pragma("unroll") for (int k = 0; k < 2; ++k) dst[n][k] = *(const PG8_LAS bf16x8*)(lds + PG8_SB(b, h) + boff + n * 2048 + k * 1024); } while (0)
; #define PG8_MMA(ai, bj, At, Bt) do { __builtin_amdgcn_s_setprio(1); _Pragma("unroll") for (int m = 0; m < 4; ++m) _Pragma("unroll") for (int n = 0; n < 2; ++n) _Pragma("unroll") for (int k = 0; k < 2; ++k) \
;         acc[ai][bj][m][n] = __builtin_amdgcn_mfma_f32_16x16x32_bf16(Bt[n][k], At[m][k], acc[ai][bj][m][n], 0, 0, 0); __builtin_amdgcn_s_setprio(0); } while (0)
; #define PG8_WAIT_V(n) asm volatile("s_waitcnt vmcnt(" #n ")" ::: "memory")
; #define PG8_WAIT_L(n) asm volatile("s_waitcnt lgkmcnt(" #n ")" ::: "memory")
; #define PG8_BAR __builtin_amdgcn_s_barrier()
; #define PG8_SCHED __builtin_amdgcn_sched_barrier(0)
; template <class Epi, class Sched, bool ALIGN_EPI = false, bool SP2 = false>
; __device__ __forceinline__ void gemm_phase(PG8_LAS unsigned char* lds, const Gemm g, const Sched& S, const Epi& E) {
;     ...
;         for (int t = 0; t < nt; t += 2) {
;     ...
;             PG8_LDB(B0, 1, 0); PG8_LDB(B1, 1, 1); PG8_SCHED; PG8_LDA(At, 1, 0); PG8_STAGE(PG8_SA(0, 1), a2 + hstep, voffA);
;             PG8_WAIT_V(8); PG8_WAIT_L(0); PG8_BAR; PG8_MMA(0, 0, At, B0); PG8_MMA(0, 1, At, B1); PG8_BAR; PG8_SCHED;
;             PG8_LDA(At, 1, 1); PG8_STAGE(PG8_SB(1, 0), b3, voffB); PG8_STAGE(PG8_SB(1, 1), b3 + hstep, voffB); PG8_STAGE(PG8_SA(1, 0), a3, voffA);
;             PG8_WAIT_V(8); PG8_WAIT_L(0); PG8_BAR; PG8_MMA(1, 0, At, B0); PG8_MMA(1, 1, At, B1); PG8_BAR; PG8_SCHED;
	s_setprio 0
	s_add_i32 s35, 16, 0x18000
	s_add_i32 s45, 16, 0x1c000
	v_add_u32_e32 v78, s35, v197
	v_add_u32_e32 v94, s45, v197
	ds_read_b128 v[58:61], v78
	ds_read_b128 v[62:65], v78 offset:1024
	ds_read_b128 v[74:77], v78 offset:2048
	ds_read_b128 v[78:81], v78 offset:3072
	ds_read_b128 v[82:85], v94
	ds_read_b128 v[86:89], v94 offset:1024
	ds_read_b128 v[90:93], v94 offset:2048
	ds_read_b128 v[94:97], v94 offset:3072
	s_add_u32 s10, s72, 0x40000
	s_addc_u32 s11, s73, 0
	s_mov_b32 m0, s3
	ds_read_b128 v[186:189], v199 offset:32768
	ds_read_b128 v[190:193], v199 offset:33792
	ds_read_b128 v[200:203], v199 offset:34816
	ds_read_b128 v[204:207], v199 offset:35840
	ds_read_b128 v[208:211], v199 offset:36864
	ds_read_b128 v[212:215], v199 offset:37888
	ds_read_b128 v[216:219], v199 offset:38912
	ds_read_b128 v[220:223], v199 offset:39936
	global_load_lds_dwordx4 v176, s[10:11]
	s_mov_b32 m0, s78
	s_nop 0
	global_load_lds_dwordx4 v178, s[10:11]
	s_waitcnt vmcnt(8)
	s_waitcnt lgkmcnt(0)
	s_setprio 1
	s_barrier
	v_mfma_f32_16x16x32_bf16 v[158:161], v[58:61], v[186:189], v[158:161]
	v_mfma_f32_16x16x32_bf16 v[154:157], v[74:77], v[186:189], v[154:157]
	v_mfma_f32_16x16x32_bf16 v[138:141], v[74:77], v[200:203], v[138:141]
	v_mfma_f32_16x16x32_bf16 v[142:145], v[58:61], v[200:203], v[142:145]
	v_mfma_f32_16x16x32_bf16 v[126:129], v[58:61], v[208:211], v[126:129]
	v_mfma_f32_16x16x32_bf16 v[122:125], v[74:77], v[208:211], v[122:125]
	v_mfma_f32_16x16x32_bf16 v[106:109], v[74:77], v[216:219], v[106:109]
	v_mfma_f32_16x16x32_bf16 v[110:113], v[58:61], v[216:219], v[110:113]
	v_mfma_f32_16x16x32_bf16 v[158:161], v[62:65], v[190:193], v[158:161]
	v_mfma_f32_16x16x32_bf16 v[154:157], v[78:81], v[190:193], v[154:157]
	v_mfma_f32_16x16x32_bf16 v[138:141], v[78:81], v[204:207], v[138:141]
	v_mfma_f32_16x16x32_bf16 v[142:145], v[62:65], v[204:207], v[142:145]
	v_mfma_f32_16x16x32_bf16 v[126:129], v[62:65], v[212:215], v[126:129]
	v_mfma_f32_16x16x32_bf16 v[122:125], v[78:81], v[212:215], v[122:125]
	v_mfma_f32_16x16x32_bf16 v[106:109], v[78:81], v[220:223], v[106:109]
	v_mfma_f32_16x16x32_bf16 v[110:113], v[62:65], v[220:223], v[110:113]
	v_mfma_f32_16x16x32_bf16 v[150:153], v[82:85], v[186:189], v[150:153]
	v_mfma_f32_16x16x32_bf16 v[146:149], v[90:93], v[186:189], v[146:149]
	v_mfma_f32_16x16x32_bf16 v[130:133], v[90:93], v[200:203], v[130:133]
	v_mfma_f32_16x16x32_bf16 v[134:137], v[82:85], v[200:203], v[134:137]
	v_mfma_f32_16x16x32_bf16 v[118:121], v[82:85], v[208:211], v[118:121]
	v_mfma_f32_16x16x32_bf16 v[114:117], v[90:93], v[208:211], v[114:117]
	v_mfma_f32_16x16x32_bf16 v[98:101], v[90:93], v[216:219], v[98:101]
	v_mfma_f32_16x16x32_bf16 v[102:105], v[82:85], v[216:219], v[102:105]
	v_mfma_f32_16x16x32_bf16 v[150:153], v[86:89], v[190:193], v[150:153]
	v_mfma_f32_16x16x32_bf16 v[146:149], v[94:97], v[190:193], v[146:149]
	v_mfma_f32_16x16x32_bf16 v[130:133], v[94:97], v[204:207], v[130:133]
	v_mfma_f32_16x16x32_bf16 v[134:137], v[86:89], v[204:207], v[134:137]
	v_mfma_f32_16x16x32_bf16 v[118:121], v[86:89], v[212:215], v[118:121]
	v_mfma_f32_16x16x32_bf16 v[114:117], v[94:97], v[212:215], v[114:117]
	v_mfma_f32_16x16x32_bf16 v[98:101], v[94:97], v[220:223], v[98:101]
	v_mfma_f32_16x16x32_bf16 v[102:105], v[86:89], v[220:223], v[102:105]
	s_barrier
	s_setprio 0
	s_add_i32 s10, s35, s76
	s_add_u32 s98, s68, s28
	s_addc_u32 s99, s69, s29
	s_mov_b32 m0, s10
	ds_read_b128 v[186:189], v199 offset:49152
	ds_read_b128 v[190:193], v199 offset:50176
	ds_read_b128 v[200:203], v199 offset:51200
	ds_read_b128 v[204:207], v199 offset:52224
	ds_read_b128 v[208:211], v199 offset:53248
	ds_read_b128 v[212:215], v199 offset:54272
	ds_read_b128 v[216:219], v199 offset:55296
	ds_read_b128 v[220:223], v199 offset:56320
	global_load_lds_dwordx4 v0, s[98:99]
	s_add_i32 m0, s10, 0x2000
	s_add_u32 s10, s68, 0x40080
	s_addc_u32 s11, s69, 0
	s_add_u32 s100, s68, s28
	s_addc_u32 s101, s69, s29
	s_add_i32 s35, s45, s76
	global_load_lds_dwordx4 v180, s[100:101]
	s_mov_b32 m0, s35
	s_nop 0
	global_load_lds_dwordx4 v0, s[10:11]
	s_add_i32 m0, s35, 0x2000
	s_nop 0
	global_load_lds_dwordx4 v180, s[10:11]
	s_add_u32 s98, s72, s28
	s_addc_u32 s99, s73, s29
	s_mov_b32 m0, s94
	s_nop 0
	global_load_lds_dwordx4 v176, s[98:99]
	s_add_u32 s100, s72, s28
	s_addc_u32 s101, s73, s29
	s_mov_b32 m0, s95
	s_nop 0
	global_load_lds_dwordx4 v178, s[100:101]
	s_waitcnt vmcnt(8)
	s_waitcnt lgkmcnt(0)
	s_setprio 1
	s_barrier
	v_mfma_f32_16x16x32_bf16 v[70:73], v[58:61], v[186:189], v[70:73]
	v_mfma_f32_16x16x32_bf16 v[66:69], v[74:77], v[186:189], v[66:69]
	v_mfma_f32_16x16x32_bf16 v[42:45], v[74:77], v[200:203], v[42:45]
	v_mfma_f32_16x16x32_bf16 v[46:49], v[58:61], v[200:203], v[46:49]
	v_mfma_f32_16x16x32_bf16 v[30:33], v[58:61], v[208:211], v[30:33]
	v_mfma_f32_16x16x32_bf16 v[26:29], v[74:77], v[208:211], v[26:29]
	v_mfma_f32_16x16x32_bf16 v[10:13], v[74:77], v[216:219], v[10:13]
	v_mfma_f32_16x16x32_bf16 v[14:17], v[58:61], v[216:219], v[14:17]
	v_mfma_f32_16x16x32_bf16 v[70:73], v[62:65], v[190:193], v[70:73]
	v_mfma_f32_16x16x32_bf16 v[66:69], v[78:81], v[190:193], v[66:69]
	v_mfma_f32_16x16x32_bf16 v[42:45], v[78:81], v[204:207], v[42:45]
	v_mfma_f32_16x16x32_bf16 v[46:49], v[62:65], v[204:207], v[46:49]
	v_mfma_f32_16x16x32_bf16 v[30:33], v[62:65], v[212:215], v[30:33]
	v_mfma_f32_16x16x32_bf16 v[26:29], v[78:81], v[212:215], v[26:29]
	v_mfma_f32_16x16x32_bf16 v[10:13], v[78:81], v[220:223], v[10:13]
	v_mfma_f32_16x16x32_bf16 v[14:17], v[62:65], v[220:223], v[14:17]
	v_mfma_f32_16x16x32_bf16 v[54:57], v[82:85], v[186:189], v[54:57]
	v_mfma_f32_16x16x32_bf16 v[50:53], v[90:93], v[186:189], v[50:53]
	v_mfma_f32_16x16x32_bf16 v[34:37], v[90:93], v[200:203], v[34:37]
	v_mfma_f32_16x16x32_bf16 v[38:41], v[82:85], v[200:203], v[38:41]
	v_mfma_f32_16x16x32_bf16 v[22:25], v[82:85], v[208:211], v[22:25]
	v_mfma_f32_16x16x32_bf16 v[18:21], v[90:93], v[208:211], v[18:21]
	v_mfma_f32_16x16x32_bf16 v[2:5], v[90:93], v[216:219], v[2:5]
	v_mfma_f32_16x16x32_bf16 v[6:9], v[82:85], v[216:219], v[6:9]
	v_mfma_f32_16x16x32_bf16 v[54:57], v[86:89], v[190:193], v[54:57]
	v_mfma_f32_16x16x32_bf16 v[50:53], v[94:97], v[190:193], v[50:53]
	v_mfma_f32_16x16x32_bf16 v[34:37], v[94:97], v[204:207], v[34:37]
	v_mfma_f32_16x16x32_bf16 v[38:41], v[86:89], v[204:207], v[38:41]
	v_mfma_f32_16x16x32_bf16 v[22:25], v[86:89], v[212:215], v[22:25]
	v_mfma_f32_16x16x32_bf16 v[18:21], v[94:97], v[212:215], v[18:21]
	v_mfma_f32_16x16x32_bf16 v[2:5], v[94:97], v[220:223], v[2:5]
	v_mfma_f32_16x16x32_bf16 v[6:9], v[86:89], v[220:223], v[6:9]
	s_barrier
	s_setprio 0
	s_add_i32 s34, s34, 2
	s_add_u32 s25, s25, 0x100
	s_addc_u32 s27, s27, 0
	s_add_u32 s42, s42, 0x100
	s_addc_u32 s43, s43, 0
	s_cmp_gt_u32 s34, 13
	s_cbranch_scc0 .LBB0_915
	s_and_b64 vcc, exec, s[20:21]
	s_cbranch_vccz .LBB0_918
	s_barrier

; #define PG8_STAGE(bufoff, gbase, voff) do { _Pragma("unroll") for (int _i = 0; _i < 2; ++_i) \
;         __builtin_amdgcn_global_load_lds((const unsigned*)((const char*)(gbase) + (voff)[_i]), (PG8_LAS unsigned*)(lds + (bufoff) + ldsw + _i * 8192), 16, 0, 0); } while (0)
; #define PG8_LDA(dst, b, h) do { _Pragma("unroll") for (int m = 0; m < 4; ++m) _Pragma("unroll") for (int k = 0; k < 2; ++k) dst[m][k] = *(const PG8_LAS bf16x8*)(lds + PG8_SA(b, h) + aoff + m * 2048 + k * 1024); } while (0)
; #define PG8_LDB(dst, b, h) do { _Pragma("unroll") for (int n = 0; n < 2; ++n) _Pragma("unroll") for (int k = 0; k < 2; ++k) dst[n][k] = *(const PG8_LAS bf16x8*)(lds + PG8_SB(b, h) + boff + n * 2048 + k * 1024); } while (0)
; #define PG8_MMA(ai, bj, At, Bt) do { __builtin_amdgcn_s_setprio(1); _Pragma("unroll") for (int m = 0; m < 4; ++m) _Pragma("unroll") for (int n = 0; n < 2; ++n) _Pragma("unroll") for (int k = 0; k < 2; ++k) \
;         acc[ai][bj][m][n] = __builtin_amdgcn_mfma_f32_16x16x32_bf16(Bt[n][k], At[m][k], acc[ai][bj][m][n], 0, 0, 0); __builtin_amdgcn_s_setprio(0); } while (0)
; #define PG8_WAIT_V(n) asm volatile("s_waitcnt vmcnt(" #n ")" ::: "memory")
; #define PG8_WAIT_L(n) asm volatile("s_waitcnt lgkmcnt(" #n ")" ::: "memory")
; template <class Epi, class Sched, bool ALIGN_EPI = false, bool SP2 = false>
; __device__ __forceinline__ void gemm_phase(PG8_LAS unsigned char* lds, const Gemm g, const Sched& S, const Epi& E) {
;     ...
;             const bool last = (t == nt - 2);
;             const char* a1 = cA + (size_t)(t + 1) * kstep;
;             const char* a2 = last ? nA : cA + (size_t)(t + 2) * kstep; const char* b2 = last ? nB : cB + (size_t)(t + 2) * kstep;
;             const char* a3 = a2 + kstep; const char* b3 = b2 + kstep;
;             if (last && has_next) S.a_ready(nxt);
;             if constexpr (SP2) {
;             PG8_LDB(B0, 0, 0); PG8_LDB(B1, 0, 1); PG8_SCHED; PG8_LDA(At, 0, 0); PG8_STAGE(PG8_SA(1, 1), a1 + hstep, voffA);
;             PG8_WAIT_V(8); PG8_WAIT_L(0); PG8_BAR; PG8_MMA(0, 0, At, B0); PG8_MMA(0, 1, At, B1); PG8_BAR; PG8_SCHED;
;             PG8_LDA(At, 0, 1); PG8_STAGE(PG8_SB(0, 0), b2, voffB); PG8_STAGE(PG8_SB(0, 1), b2 + hstep, voffB); PG8_STAGE(PG8_SA(0, 0), a2, voffA);
;             PG8_WAIT_V(8); PG8_WAIT_L(0); PG8_BAR; PG8_MMA(1, 0, At, B0); PG8_MMA(1, 1, At, B1); PG8_BAR; PG8_SCHED;
.LBB0_1033:
	s_add_u32 s10, s50, 0xfffc0080
	s_addc_u32 s11, s51, -1
	s_add_i32 s69, 16, 0x10000
	s_cmp_eq_u32 s68, 12
	s_cselect_b32 s61, s34, s11
	s_cselect_b32 s60, s35, s10
	s_cselect_b32 s59, s27, s67
	s_cselect_b32 s58, s43, s66
	s_add_i32 s72, 16, 0x14000
	v_add_u32_e32 v142, s69, v177
	v_add_u32_e32 v188, s72, v177
	ds_read_b128 v[130:133], v142
	ds_read_b128 v[134:137], v142 offset:1024
	ds_read_b128 v[138:141], v142 offset:2048
	ds_read_b128 v[142:145], v142 offset:3072
	ds_read_b128 v[158:161], v188
	ds_read_b128 v[180:183], v188 offset:1024
	ds_read_b128 v[184:187], v188 offset:2048
	ds_read_b128 v[188:191], v188 offset:3072
	s_add_i32 m0, s9, 0xc000
	ds_read_b128 v[192:195], v179
	ds_read_b128 v[196:199], v179 offset:1024
	ds_read_b128 v[200:203], v179 offset:2048
	ds_read_b128 v[204:207], v179 offset:3072
	ds_read_b128 v[208:211], v179 offset:4096
	ds_read_b128 v[212:215], v179 offset:5120
	ds_read_b128 v[216:219], v179 offset:6144
	ds_read_b128 v[220:223], v179 offset:7168
	global_load_lds_dwordx4 v156, s[50:51]
	s_add_i32 m0, s9, 0xe000
	s_nop 0
	global_load_lds_dwordx4 v154, s[50:51]
	s_waitcnt vmcnt(8)
	s_waitcnt lgkmcnt(0)
	s_setprio 1
	s_barrier
	v_mfma_f32_16x16x32_bf16 v[126:129], v[130:133], v[192:195], v[126:129]
	v_mfma_f32_16x16x32_bf16 v[122:125], v[138:141], v[192:195], v[122:125]
	v_mfma_f32_16x16x32_bf16 v[106:109], v[138:141], v[200:203], v[106:109]
	v_mfma_f32_16x16x32_bf16 v[110:113], v[130:133], v[200:203], v[110:113]
	v_mfma_f32_16x16x32_bf16 v[94:97], v[130:133], v[208:211], v[94:97]
	v_mfma_f32_16x16x32_bf16 v[90:93], v[138:141], v[208:211], v[90:93]
	v_mfma_f32_16x16x32_bf16 v[74:77], v[138:141], v[216:219], v[74:77]
	v_mfma_f32_16x16x32_bf16 v[78:81], v[130:133], v[216:219], v[78:81]
	v_mfma_f32_16x16x32_bf16 v[126:129], v[134:137], v[196:199], v[126:129]
	v_mfma_f32_16x16x32_bf16 v[122:125], v[142:145], v[196:199], v[122:125]
	v_mfma_f32_16x16x32_bf16 v[106:109], v[142:145], v[204:207], v[106:109]
	v_mfma_f32_16x16x32_bf16 v[110:113], v[134:137], v[204:207], v[110:113]
	v_mfma_f32_16x16x32_bf16 v[94:97], v[134:137], v[212:215], v[94:97]
	v_mfma_f32_16x16x32_bf16 v[90:93], v[142:145], v[212:215], v[90:93]
	v_mfma_f32_16x16x32_bf16 v[74:77], v[142:145], v[220:223], v[74:77]
	v_mfma_f32_16x16x32_bf16 v[78:81], v[134:137], v[220:223], v[78:81]
	v_mfma_f32_16x16x32_bf16 v[118:121], v[158:161], v[192:195], v[118:121]
	v_mfma_f32_16x16x32_bf16 v[114:117], v[184:187], v[192:195], v[114:117]
	v_mfma_f32_16x16x32_bf16 v[98:101], v[184:187], v[200:203], v[98:101]
	v_mfma_f32_16x16x32_bf16 v[102:105], v[158:161], v[200:203], v[102:105]
	v_mfma_f32_16x16x32_bf16 v[86:89], v[158:161], v[208:211], v[86:89]
	v_mfma_f32_16x16x32_bf16 v[82:85], v[184:187], v[208:211], v[82:85]
	v_mfma_f32_16x16x32_bf16 v[66:69], v[184:187], v[216:219], v[66:69]
	v_mfma_f32_16x16x32_bf16 v[70:73], v[158:161], v[216:219], v[70:73]
	v_mfma_f32_16x16x32_bf16 v[118:121], v[180:183], v[196:199], v[118:121]
	v_mfma_f32_16x16x32_bf16 v[114:117], v[188:191], v[196:199], v[114:117]
	v_mfma_f32_16x16x32_bf16 v[98:101], v[188:191], v[204:207], v[98:101]
	v_mfma_f32_16x16x32_bf16 v[102:105], v[180:183], v[204:207], v[102:105]
	v_mfma_f32_16x16x32_bf16 v[86:89], v[180:183], v[212:215], v[86:89]
	v_mfma_f32_16x16x32_bf16 v[82:85], v[188:191], v[212:215], v[82:85]
	v_mfma_f32_16x16x32_bf16 v[66:69], v[188:191], v[220:223], v[66:69]
	v_mfma_f32_16x16x32_bf16 v[70:73], v[180:183], v[220:223], v[70:73]
	s_barrier
	s_setprio 0
	s_add_i32 s10, s69, s6
	s_mov_b32 m0, s10
	ds_read_b128 v[192:195], v179 offset:16384
	ds_read_b128 v[196:199], v179 offset:17408
	ds_read_b128 v[200:203], v179 offset:18432
	ds_read_b128 v[204:207], v179 offset:19456
	ds_read_b128 v[208:211], v179 offset:20480
	ds_read_b128 v[212:215], v179 offset:21504
	ds_read_b128 v[216:219], v179 offset:22528
	ds_read_b128 v[220:223], v179 offset:23552
	global_load_lds_dwordx4 v0, s[58:59]
	s_add_i32 m0, s10, 0x2000
	s_add_u32 s10, s58, 0x40000
	s_addc_u32 s11, s59, 0
	s_add_i32 s69, s72, s6
	global_load_lds_dwordx4 v146, s[58:59]
	s_mov_b32 m0, s69
	s_nop 0
	global_load_lds_dwordx4 v0, s[10:11]
	s_add_i32 m0, s69, 0x2000
	s_nop 0
	global_load_lds_dwordx4 v146, s[10:11]
	s_mov_b32 m0, s9
	s_nop 0
	global_load_lds_dwordx4 v150, s[60:61]
	s_mov_b32 m0, s54
	s_nop 0
	global_load_lds_dwordx4 v148, s[60:61]
	s_waitcnt vmcnt(8)
	s_waitcnt lgkmcnt(0)
	s_setprio 1
	s_barrier
	v_mfma_f32_16x16x32_bf16 v[62:65], v[130:133], v[192:195], v[62:65]
	v_mfma_f32_16x16x32_bf16 v[58:61], v[138:141], v[192:195], v[58:61]
	v_mfma_f32_16x16x32_bf16 v[42:45], v[138:141], v[200:203], v[42:45]
	v_mfma_f32_16x16x32_bf16 v[46:49], v[130:133], v[200:203], v[46:49]
	v_mfma_f32_16x16x32_bf16 v[30:33], v[130:133], v[208:211], v[30:33]
	v_mfma_f32_16x16x32_bf16 v[26:29], v[138:141], v[208:211], v[26:29]
	v_mfma_f32_16x16x32_bf16 v[10:13], v[138:141], v[216:219], v[10:13]
	v_mfma_f32_16x16x32_bf16 v[14:17], v[130:133], v[216:219], v[14:17]
	v_mfma_f32_16x16x32_bf16 v[62:65], v[134:137], v[196:199], v[62:65]
	v_mfma_f32_16x16x32_bf16 v[58:61], v[142:145], v[196:199], v[58:61]
	v_mfma_f32_16x16x32_bf16 v[42:45], v[142:145], v[204:207], v[42:45]
	v_mfma_f32_16x16x32_bf16 v[46:49], v[134:137], v[204:207], v[46:49]
	v_mfma_f32_16x16x32_bf16 v[30:33], v[134:137], v[212:215], v[30:33]
	v_mfma_f32_16x16x32_bf16 v[26:29], v[142:145], v[212:215], v[26:29]
	v_mfma_f32_16x16x32_bf16 v[10:13], v[142:145], v[220:223], v[10:13]
	v_mfma_f32_16x16x32_bf16 v[14:17], v[134:137], v[220:223], v[14:17]
	v_mfma_f32_16x16x32_bf16 v[54:57], v[158:161], v[192:195], v[54:57]
	v_mfma_f32_16x16x32_bf16 v[50:53], v[184:187], v[192:195], v[50:53]
	v_mfma_f32_16x16x32_bf16 v[34:37], v[184:187], v[200:203], v[34:37]
	v_mfma_f32_16x16x32_bf16 v[38:41], v[158:161], v[200:203], v[38:41]
	v_mfma_f32_16x16x32_bf16 v[22:25], v[158:161], v[208:211], v[22:25]
	v_mfma_f32_16x16x32_bf16 v[18:21], v[184:187], v[208:211], v[18:21]
	v_mfma_f32_16x16x32_bf16 v[2:5], v[184:187], v[216:219], v[2:5]
	v_mfma_f32_16x16x32_bf16 v[6:9], v[158:161], v[216:219], v[6:9]
	v_mfma_f32_16x16x32_bf16 v[54:57], v[180:183], v[196:199], v[54:57]
	v_mfma_f32_16x16x32_bf16 v[50:53], v[188:191], v[196:199], v[50:53]
	v_mfma_f32_16x16x32_bf16 v[34:37], v[188:191], v[204:207], v[34:37]
	v_mfma_f32_16x16x32_bf16 v[38:41], v[180:183], v[204:207], v[38:41]
	v_mfma_f32_16x16x32_bf16 v[22:25], v[180:183], v[212:215], v[22:25]
	v_mfma_f32_16x16x32_bf16 v[18:21], v[188:191], v[212:215], v[18:21]
	v_mfma_f32_16x16x32_bf16 v[2:5], v[188:191], v[220:223], v[2:5]
	v_mfma_f32_16x16x32_bf16 v[6:9], v[180:183], v[220:223], v[6:9]
	s_barrier
; #define PG8_STAGE(bufoff, gbase, voff) do { _Pragma("unroll") for (int _i = 0; _i < 2; ++_i) \
;         __builtin_amdgcn_global_load_lds((const unsigned*)((const char*)(gbase) + (voff)[_i]), (PG8_LAS unsigned*)(lds + (bufoff) + ldsw + _i * 8192), 16, 0, 0); } while (0)
; #define PG8_LDA(dst, b, h) do { _Pragma("unroll") for (int m = 0; m < 4; ++m) _Pragma("unroll") for (int k = 0; k < 2; ++k) dst[m][k] = *(const PG8_LAS bf16x8*)(lds + PG8_SA(b, h) + aoff + m * 2048 + k * 1024); } while (0)
; #define PG8_LDB(dst, b, h) do { _Pragma("unroll") for (int n = 0; n < 2; ++n) _Pragma("unroll") for (int k = 0; k < 2; ++k) dst[n][k] = *(const PG8_LAS bf16x8*)(lds + PG8_SB(b, h) + boff + n * 2048 + k * 1024); } while (0)
; #define PG8_MMA(ai, bj, At, Bt) do { __builtin_amdgcn_s_setprio(1); _Pragma("unroll") for (int m = 0; m < 4; ++m) _Pragma("unroll") for (int n = 0; n < 2; ++n) _Pragma("unroll") for (int k = 0; k < 2; ++k) \
;         acc[ai][bj][m][n] = __builtin_amdgcn_mfma_f32_16x16x32_bf16(Bt[n][k], At[m][k], acc[ai][bj][m][n], 0, 0, 0); __builtin_amdgcn_s_setprio(0); } while (0)
; #define PG8_WAIT_V(n) asm volatile("s_waitcnt vmcnt(" #n ")" ::: "memory")
; #define PG8_WAIT_L(n) asm volatile("s_waitcnt lgkmcnt(" #n ")" ::: "memory")
; #define PG8_BAR __builtin_amdgcn_s_barrier()
; #define PG8_SCHED __builtin_amdgcn_sched_barrier(0)
; template <class Epi, class Sched, bool ALIGN_EPI = false, bool SP2 = false>
; __device__ __forceinline__ void gemm_phase(PG8_LAS unsigned char* lds, const Gemm g, const Sched& S, const Epi& E) {
;     ...
;         for (int t = 0; t < nt; t += 2) {
;     ...
;             PG8_LDB(B0, 1, 0); PG8_LDB(B1, 1, 1); PG8_SCHED; PG8_LDA(At, 1, 0); PG8_STAGE(PG8_SA(0, 1), a2 + hstep, voffA);
;             PG8_WAIT_V(8); PG8_WAIT_L(0); PG8_BAR; PG8_MMA(0, 0, At, B0); PG8_MMA(0, 1, At, B1); PG8_BAR; PG8_SCHED;
;             PG8_LDA(At, 1, 1); PG8_STAGE(PG8_SB(1, 0), b3, voffB); PG8_STAGE(PG8_SB(1, 1), b3 + hstep, voffB); PG8_STAGE(PG8_SA(1, 0), a3, voffA);
;             PG8_WAIT_V(8); PG8_WAIT_L(0); PG8_BAR; PG8_MMA(1, 0, At, B0); PG8_MMA(1, 1, At, B1); PG8_BAR; PG8_SCHED;
	s_setprio 0
	s_add_i32 s69, 16, 0x18000
	s_add_i32 s72, 16, 0x1c000
	v_add_u32_e32 v142, s69, v177
	v_add_u32_e32 v188, s72, v177
	ds_read_b128 v[130:133], v142
	ds_read_b128 v[134:137], v142 offset:1024
	ds_read_b128 v[138:141], v142 offset:2048
	ds_read_b128 v[142:145], v142 offset:3072
	ds_read_b128 v[158:161], v188
	ds_read_b128 v[180:183], v188 offset:1024
	ds_read_b128 v[184:187], v188 offset:2048
	ds_read_b128 v[188:191], v188 offset:3072
	s_add_u32 s10, s60, 0x40000
	s_addc_u32 s11, s61, 0
	s_mov_b32 m0, s55
	ds_read_b128 v[192:195], v179 offset:32768
	ds_read_b128 v[196:199], v179 offset:33792
	ds_read_b128 v[200:203], v179 offset:34816
	ds_read_b128 v[204:207], v179 offset:35840
	ds_read_b128 v[208:211], v179 offset:36864
	ds_read_b128 v[212:215], v179 offset:37888
	ds_read_b128 v[216:219], v179 offset:38912
	ds_read_b128 v[220:223], v179 offset:39936
	global_load_lds_dwordx4 v150, s[10:11]
	s_mov_b32 m0, s56
	s_nop 0
	global_load_lds_dwordx4 v148, s[10:11]
	s_waitcnt vmcnt(8)
	s_waitcnt lgkmcnt(0)
	s_setprio 1
	s_barrier
	v_mfma_f32_16x16x32_bf16 v[126:129], v[130:133], v[192:195], v[126:129]
	v_mfma_f32_16x16x32_bf16 v[122:125], v[138:141], v[192:195], v[122:125]
	v_mfma_f32_16x16x32_bf16 v[106:109], v[138:141], v[200:203], v[106:109]
	v_mfma_f32_16x16x32_bf16 v[110:113], v[130:133], v[200:203], v[110:113]
	v_mfma_f32_16x16x32_bf16 v[94:97], v[130:133], v[208:211], v[94:97]
	v_mfma_f32_16x16x32_bf16 v[90:93], v[138:141], v[208:211], v[90:93]
	v_mfma_f32_16x16x32_bf16 v[74:77], v[138:141], v[216:219], v[74:77]
	v_mfma_f32_16x16x32_bf16 v[78:81], v[130:133], v[216:219], v[78:81]
	v_mfma_f32_16x16x32_bf16 v[126:129], v[134:137], v[196:199], v[126:129]
	v_mfma_f32_16x16x32_bf16 v[122:125], v[142:145], v[196:199], v[122:125]
	v_mfma_f32_16x16x32_bf16 v[106:109], v[142:145], v[204:207], v[106:109]
	v_mfma_f32_16x16x32_bf16 v[110:113], v[134:137], v[204:207], v[110:113]
	v_mfma_f32_16x16x32_bf16 v[94:97], v[134:137], v[212:215], v[94:97]
	v_mfma_f32_16x16x32_bf16 v[90:93], v[142:145], v[212:215], v[90:93]
	v_mfma_f32_16x16x32_bf16 v[74:77], v[142:145], v[220:223], v[74:77]
	v_mfma_f32_16x16x32_bf16 v[78:81], v[134:137], v[220:223], v[78:81]
	v_mfma_f32_16x16x32_bf16 v[118:121], v[158:161], v[192:195], v[118:121]
	v_mfma_f32_16x16x32_bf16 v[114:117], v[184:187], v[192:195], v[114:117]
	v_mfma_f32_16x16x32_bf16 v[98:101], v[184:187], v[200:203], v[98:101]
	v_mfma_f32_16x16x32_bf16 v[102:105], v[158:161], v[200:203], v[102:105]
	v_mfma_f32_16x16x32_bf16 v[86:89], v[158:161], v[208:211], v[86:89]
	v_mfma_f32_16x16x32_bf16 v[82:85], v[184:187], v[208:211], v[82:85]
	v_mfma_f32_16x16x32_bf16 v[66:69], v[184:187], v[216:219], v[66:69]
	v_mfma_f32_16x16x32_bf16 v[70:73], v[158:161], v[216:219], v[70:73]
	v_mfma_f32_16x16x32_bf16 v[118:121], v[180:183], v[196:199], v[118:121]
	v_mfma_f32_16x16x32_bf16 v[114:117], v[188:191], v[196:199], v[114:117]
	v_mfma_f32_16x16x32_bf16 v[98:101], v[188:191], v[204:207], v[98:101]
	v_mfma_f32_16x16x32_bf16 v[102:105], v[180:183], v[204:207], v[102:105]
	v_mfma_f32_16x16x32_bf16 v[86:89], v[180:183], v[212:215], v[86:89]
	v_mfma_f32_16x16x32_bf16 v[82:85], v[188:191], v[212:215], v[82:85]
	v_mfma_f32_16x16x32_bf16 v[66:69], v[188:191], v[220:223], v[66:69]
	v_mfma_f32_16x16x32_bf16 v[70:73], v[180:183], v[220:223], v[70:73]
	s_barrier
	s_setprio 0
	s_add_i32 s10, s69, s6
	s_add_u32 s98, s58, s28
	s_addc_u32 s99, s59, s29
	s_mov_b32 m0, s10
	ds_read_b128 v[192:195], v179 offset:49152
	ds_read_b128 v[196:199], v179 offset:50176
	ds_read_b128 v[200:203], v179 offset:51200
	ds_read_b128 v[204:207], v179 offset:52224
	ds_read_b128 v[208:211], v179 offset:53248
	ds_read_b128 v[212:215], v179 offset:54272
	ds_read_b128 v[216:219], v179 offset:55296
	ds_read_b128 v[220:223], v179 offset:56320
	global_load_lds_dwordx4 v0, s[98:99]
	s_add_i32 m0, s10, 0x2000
	s_add_u32 s10, s58, 0x40080
	s_addc_u32 s11, s59, 0
	s_add_u32 s100, s58, s28
	s_addc_u32 s101, s59, s29
	s_add_i32 s58, s72, s6
	global_load_lds_dwordx4 v146, s[100:101]
	s_mov_b32 m0, s58
	s_nop 0
	global_load_lds_dwordx4 v0, s[10:11]
	s_add_i32 m0, s58, 0x2000
	s_nop 0
	global_load_lds_dwordx4 v146, s[10:11]
	s_add_u32 s98, s60, s28
	s_addc_u32 s99, s61, s29
	s_mov_b32 m0, s63
	s_nop 0
	global_load_lds_dwordx4 v150, s[98:99]
	s_add_u32 s100, s60, s28
	s_addc_u32 s101, s61, s29
	s_mov_b32 m0, s64
	s_nop 0
	global_load_lds_dwordx4 v148, s[100:101]
	s_waitcnt vmcnt(8)
	s_waitcnt lgkmcnt(0)
	s_setprio 1
	s_barrier
	v_mfma_f32_16x16x32_bf16 v[62:65], v[130:133], v[192:195], v[62:65]
	v_mfma_f32_16x16x32_bf16 v[58:61], v[138:141], v[192:195], v[58:61]
	v_mfma_f32_16x16x32_bf16 v[42:45], v[138:141], v[200:203], v[42:45]
	v_mfma_f32_16x16x32_bf16 v[46:49], v[130:133], v[200:203], v[46:49]
	v_mfma_f32_16x16x32_bf16 v[30:33], v[130:133], v[208:211], v[30:33]
	v_mfma_f32_16x16x32_bf16 v[26:29], v[138:141], v[208:211], v[26:29]
	v_mfma_f32_16x16x32_bf16 v[10:13], v[138:141], v[216:219], v[10:13]
	v_mfma_f32_16x16x32_bf16 v[14:17], v[130:133], v[216:219], v[14:17]
	v_mfma_f32_16x16x32_bf16 v[62:65], v[134:137], v[196:199], v[62:65]
	v_mfma_f32_16x16x32_bf16 v[58:61], v[142:145], v[196:199], v[58:61]
	v_mfma_f32_16x16x32_bf16 v[42:45], v[142:145], v[204:207], v[42:45]
	v_mfma_f32_16x16x32_bf16 v[46:49], v[134:137], v[204:207], v[46:49]
	v_mfma_f32_16x16x32_bf16 v[30:33], v[134:137], v[212:215], v[30:33]
	v_mfma_f32_16x16x32_bf16 v[26:29], v[142:145], v[212:215], v[26:29]
	v_mfma_f32_16x16x32_bf16 v[10:13], v[142:145], v[220:223], v[10:13]
	v_mfma_f32_16x16x32_bf16 v[14:17], v[134:137], v[220:223], v[14:17]
	v_mfma_f32_16x16x32_bf16 v[54:57], v[158:161], v[192:195], v[54:57]
	v_mfma_f32_16x16x32_bf16 v[50:53], v[184:187], v[192:195], v[50:53]
	v_mfma_f32_16x16x32_bf16 v[34:37], v[184:187], v[200:203], v[34:37]
	v_mfma_f32_16x16x32_bf16 v[38:41], v[158:161], v[200:203], v[38:41]
	v_mfma_f32_16x16x32_bf16 v[22:25], v[158:161], v[208:211], v[22:25]
	v_mfma_f32_16x16x32_bf16 v[18:21], v[184:187], v[208:211], v[18:21]
	v_mfma_f32_16x16x32_bf16 v[2:5], v[184:187], v[216:219], v[2:5]
	v_mfma_f32_16x16x32_bf16 v[6:9], v[158:161], v[216:219], v[6:9]
	v_mfma_f32_16x16x32_bf16 v[54:57], v[180:183], v[196:199], v[54:57]
	v_mfma_f32_16x16x32_bf16 v[50:53], v[188:191], v[196:199], v[50:53]
	v_mfma_f32_16x16x32_bf16 v[34:37], v[188:191], v[204:207], v[34:37]
	v_mfma_f32_16x16x32_bf16 v[38:41], v[180:183], v[204:207], v[38:41]
	v_mfma_f32_16x16x32_bf16 v[22:25], v[180:183], v[212:215], v[22:25]
	v_mfma_f32_16x16x32_bf16 v[18:21], v[188:191], v[212:215], v[18:21]
	v_mfma_f32_16x16x32_bf16 v[2:5], v[188:191], v[220:223], v[2:5]
	v_mfma_f32_16x16x32_bf16 v[6:9], v[180:183], v[220:223], v[6:9]
	s_barrier
	s_setprio 0
	s_add_i32 s68, s68, 2
	s_add_u32 s66, s66, 0x100
	s_addc_u32 s67, s67, 0
	s_add_u32 s50, s50, 0x100
	s_addc_u32 s51, s51, 0
	s_cmp_gt_u32 s68, 13
	s_cbranch_scc0 .LBB0_1033
	s_and_b64 vcc, exec, s[24:25]
	s_cbranch_vccz .LBB0_1036
	s_barrier

; #define PG8_STAGE(bufoff, gbase, voff) do { _Pragma("unroll") for (int _i = 0; _i < 2; ++_i) \
;         __builtin_amdgcn_global_load_lds((const unsigned*)((const char*)(gbase) + (voff)[_i]), (PG8_LAS unsigned*)(lds + (bufoff) + ldsw + _i * 8192), 16, 0, 0); } while (0)
; #define PG8_LDA(dst, b, h) do { _Pragma("unroll") for (int m = 0; m < 4; ++m) _Pragma("unroll") for (int k = 0; k < 2; ++k) dst[m][k] = *(const PG8_LAS bf16x8*)(lds + PG8_SA(b, h) + aoff + m * 2048 + k * 1024); } while (0)
; #define PG8_LDB(dst, b, h) do { _Pragma("unroll") for (int n = 0; n < 2; ++n) _Pragma("unroll") for (int k = 0; k < 2; ++k) dst[n][k] = *(const PG8_LAS bf16x8*)(lds + PG8_SB(b, h) + boff + n * 2048 + k * 1024); } while (0)
; #define PG8_MMA(ai, bj, At, Bt) do { __builtin_amdgcn_s_setprio(1); _Pragma("unroll") for (int m = 0; m < 4; ++m) _Pragma("unroll") for (int n = 0; n < 2; ++n) _Pragma("unroll") for (int k = 0; k < 2; ++k) \
;         acc[ai][bj][m][n] = __builtin_amdgcn_mfma_f32_16x16x32_bf16(Bt[n][k], At[m][k], acc[ai][bj][m][n], 0, 0, 0); __builtin_amdgcn_s_setprio(0); } while (0)
; #define PG8_WAIT_V(n) asm volatile("s_waitcnt vmcnt(" #n ")" ::: "memory")
; #define PG8_WAIT_L(n) asm volatile("s_waitcnt lgkmcnt(" #n ")" ::: "memory")
; template <class Epi, class Sched, bool ALIGN_EPI = false, bool SP2 = false>
; __device__ __forceinline__ void gemm_phase(PG8_LAS unsigned char* lds, const Gemm g, const Sched& S, const Epi& E) {
;     ...
;             const bool last = (t == nt - 2);
;             const char* a1 = cA + (size_t)(t + 1) * kstep;
;             const char* a2 = last ? nA : cA + (size_t)(t + 2) * kstep; const char* b2 = last ? nB : cB + (size_t)(t + 2) * kstep;
;             const char* a3 = a2 + kstep; const char* b3 = b2 + kstep;
;             if (last && has_next) S.a_ready(nxt);
;             if constexpr (SP2) {
;             PG8_LDB(B0, 0, 0); PG8_LDB(B1, 0, 1); PG8_SCHED; PG8_LDA(At, 0, 0); PG8_STAGE(PG8_SA(1, 1), a1 + hstep, voffA);
;             PG8_WAIT_V(8); PG8_WAIT_L(0); PG8_BAR; PG8_MMA(0, 0, At, B0); PG8_MMA(0, 1, At, B1); PG8_BAR; PG8_SCHED;
;             PG8_LDA(At, 0, 1); PG8_STAGE(PG8_SB(0, 0), b2, voffB); PG8_STAGE(PG8_SB(0, 1), b2 + hstep, voffB); PG8_STAGE(PG8_SA(0, 0), a2, voffA);
;             PG8_WAIT_V(8); PG8_WAIT_L(0); PG8_BAR; PG8_MMA(1, 0, At, B0); PG8_MMA(1, 1, At, B1); PG8_BAR; PG8_SCHED;
.LBB0_1275:
	s_add_u32 s10, s40, 0xfffc0080
	s_addc_u32 s11, s41, -1
	s_add_i32 s64, 16, 0x10000
	s_cmp_eq_u32 s63, 12
	s_cselect_b32 s51, s34, s11
	s_cselect_b32 s50, s35, s10
	s_cselect_b32 s49, s27, s62
	s_cselect_b32 s48, s43, s59
	s_add_i32 s65, 16, 0x14000
	v_add_u32_e32 v142, s64, v179
	v_add_u32_e32 v176, s65, v179
	ds_read_b128 v[130:133], v142
	ds_read_b128 v[134:137], v142 offset:1024
	ds_read_b128 v[138:141], v142 offset:2048
	ds_read_b128 v[142:145], v142 offset:3072
	ds_read_b128 v[158:161], v176
	ds_read_b128 v[182:185], v176 offset:1024
	ds_read_b128 v[186:189], v176 offset:2048
	ds_read_b128 v[190:193], v176 offset:3072
	s_add_i32 m0, s4, 0xc000
	ds_read_b128 v[194:197], v181
	ds_read_b128 v[198:201], v181 offset:1024
	ds_read_b128 v[202:205], v181 offset:2048
	ds_read_b128 v[206:209], v181 offset:3072
	ds_read_b128 v[210:213], v181 offset:4096
	ds_read_b128 v[214:217], v181 offset:5120
	ds_read_b128 v[218:221], v181 offset:6144
	ds_read_b128 v[222:225], v181 offset:7168
	global_load_lds_dwordx4 v156, s[40:41]
	s_add_i32 m0, s4, 0xe000
	s_nop 0
	global_load_lds_dwordx4 v154, s[40:41]
	s_waitcnt vmcnt(8)
	s_waitcnt lgkmcnt(0)
	s_setprio 1
	s_barrier
	v_mfma_f32_16x16x32_bf16 v[126:129], v[130:133], v[194:197], v[126:129]
	v_mfma_f32_16x16x32_bf16 v[122:125], v[138:141], v[194:197], v[122:125]
	v_mfma_f32_16x16x32_bf16 v[106:109], v[138:141], v[202:205], v[106:109]
	v_mfma_f32_16x16x32_bf16 v[110:113], v[130:133], v[202:205], v[110:113]
	v_mfma_f32_16x16x32_bf16 v[94:97], v[130:133], v[210:213], v[94:97]
	v_mfma_f32_16x16x32_bf16 v[90:93], v[138:141], v[210:213], v[90:93]
	v_mfma_f32_16x16x32_bf16 v[74:77], v[138:141], v[218:221], v[74:77]
	v_mfma_f32_16x16x32_bf16 v[78:81], v[130:133], v[218:221], v[78:81]
	v_mfma_f32_16x16x32_bf16 v[126:129], v[134:137], v[198:201], v[126:129]
	v_mfma_f32_16x16x32_bf16 v[122:125], v[142:145], v[198:201], v[122:125]
	v_mfma_f32_16x16x32_bf16 v[106:109], v[142:145], v[206:209], v[106:109]
	v_mfma_f32_16x16x32_bf16 v[110:113], v[134:137], v[206:209], v[110:113]
	v_mfma_f32_16x16x32_bf16 v[94:97], v[134:137], v[214:217], v[94:97]
	v_mfma_f32_16x16x32_bf16 v[90:93], v[142:145], v[214:217], v[90:93]
	v_mfma_f32_16x16x32_bf16 v[74:77], v[142:145], v[222:225], v[74:77]
	v_mfma_f32_16x16x32_bf16 v[78:81], v[134:137], v[222:225], v[78:81]
	v_mfma_f32_16x16x32_bf16 v[118:121], v[158:161], v[194:197], v[118:121]
	v_mfma_f32_16x16x32_bf16 v[114:117], v[186:189], v[194:197], v[114:117]
	v_mfma_f32_16x16x32_bf16 v[98:101], v[186:189], v[202:205], v[98:101]
	v_mfma_f32_16x16x32_bf16 v[102:105], v[158:161], v[202:205], v[102:105]
	v_mfma_f32_16x16x32_bf16 v[86:89], v[158:161], v[210:213], v[86:89]
	v_mfma_f32_16x16x32_bf16 v[82:85], v[186:189], v[210:213], v[82:85]
	v_mfma_f32_16x16x32_bf16 v[66:69], v[186:189], v[218:221], v[66:69]
	v_mfma_f32_16x16x32_bf16 v[70:73], v[158:161], v[218:221], v[70:73]
	v_mfma_f32_16x16x32_bf16 v[118:121], v[182:185], v[198:201], v[118:121]
	v_mfma_f32_16x16x32_bf16 v[114:117], v[190:193], v[198:201], v[114:117]
	v_mfma_f32_16x16x32_bf16 v[98:101], v[190:193], v[206:209], v[98:101]
	v_mfma_f32_16x16x32_bf16 v[102:105], v[182:185], v[206:209], v[102:105]
	v_mfma_f32_16x16x32_bf16 v[86:89], v[182:185], v[214:217], v[86:89]
	v_mfma_f32_16x16x32_bf16 v[82:85], v[190:193], v[214:217], v[82:85]
	v_mfma_f32_16x16x32_bf16 v[66:69], v[190:193], v[222:225], v[66:69]
	v_mfma_f32_16x16x32_bf16 v[70:73], v[182:185], v[222:225], v[70:73]
	s_barrier
	s_setprio 0
	s_add_i32 s10, s64, s3
	s_mov_b32 m0, s10
	ds_read_b128 v[194:197], v181 offset:16384
	ds_read_b128 v[198:201], v181 offset:17408
	ds_read_b128 v[202:205], v181 offset:18432
	ds_read_b128 v[206:209], v181 offset:19456
	ds_read_b128 v[210:213], v181 offset:20480
	ds_read_b128 v[214:217], v181 offset:21504
	ds_read_b128 v[218:221], v181 offset:22528
	ds_read_b128 v[222:225], v181 offset:23552
	global_load_lds_dwordx4 v0, s[48:49]
	s_add_i32 m0, s10, 0x2000
	s_add_u32 s10, s48, 0x40000
	s_addc_u32 s11, s49, 0
	s_add_i32 s64, s65, s3
	global_load_lds_dwordx4 v146, s[48:49]
	s_mov_b32 m0, s64
	s_nop 0
	global_load_lds_dwordx4 v0, s[10:11]
	s_add_i32 m0, s64, 0x2000
	s_nop 0
	global_load_lds_dwordx4 v146, s[10:11]
	s_mov_b32 m0, s4
	s_nop 0
	global_load_lds_dwordx4 v150, s[50:51]
	s_mov_b32 m0, s5
	s_nop 0
	global_load_lds_dwordx4 v148, s[50:51]
	s_waitcnt vmcnt(8)
	s_waitcnt lgkmcnt(0)
	s_setprio 1
	s_barrier
	v_mfma_f32_16x16x32_bf16 v[62:65], v[130:133], v[194:197], v[62:65]
	v_mfma_f32_16x16x32_bf16 v[58:61], v[138:141], v[194:197], v[58:61]
	v_mfma_f32_16x16x32_bf16 v[42:45], v[138:141], v[202:205], v[42:45]
	v_mfma_f32_16x16x32_bf16 v[46:49], v[130:133], v[202:205], v[46:49]
	v_mfma_f32_16x16x32_bf16 v[30:33], v[130:133], v[210:213], v[30:33]
	v_mfma_f32_16x16x32_bf16 v[26:29], v[138:141], v[210:213], v[26:29]
	v_mfma_f32_16x16x32_bf16 v[10:13], v[138:141], v[218:221], v[10:13]
	v_mfma_f32_16x16x32_bf16 v[14:17], v[130:133], v[218:221], v[14:17]
	v_mfma_f32_16x16x32_bf16 v[62:65], v[134:137], v[198:201], v[62:65]
	v_mfma_f32_16x16x32_bf16 v[58:61], v[142:145], v[198:201], v[58:61]
	v_mfma_f32_16x16x32_bf16 v[42:45], v[142:145], v[206:209], v[42:45]
	v_mfma_f32_16x16x32_bf16 v[46:49], v[134:137], v[206:209], v[46:49]
	v_mfma_f32_16x16x32_bf16 v[30:33], v[134:137], v[214:217], v[30:33]
	v_mfma_f32_16x16x32_bf16 v[26:29], v[142:145], v[214:217], v[26:29]
	v_mfma_f32_16x16x32_bf16 v[10:13], v[142:145], v[222:225], v[10:13]
	v_mfma_f32_16x16x32_bf16 v[14:17], v[134:137], v[222:225], v[14:17]
	v_mfma_f32_16x16x32_bf16 v[54:57], v[158:161], v[194:197], v[54:57]
	v_mfma_f32_16x16x32_bf16 v[50:53], v[186:189], v[194:197], v[50:53]
	v_mfma_f32_16x16x32_bf16 v[34:37], v[186:189], v[202:205], v[34:37]
	v_mfma_f32_16x16x32_bf16 v[38:41], v[158:161], v[202:205], v[38:41]
	v_mfma_f32_16x16x32_bf16 v[22:25], v[158:161], v[210:213], v[22:25]
	v_mfma_f32_16x16x32_bf16 v[18:21], v[186:189], v[210:213], v[18:21]
	v_mfma_f32_16x16x32_bf16 v[2:5], v[186:189], v[218:221], v[2:5]
	v_mfma_f32_16x16x32_bf16 v[6:9], v[158:161], v[218:221], v[6:9]
	v_mfma_f32_16x16x32_bf16 v[54:57], v[182:185], v[198:201], v[54:57]
	v_mfma_f32_16x16x32_bf16 v[50:53], v[190:193], v[198:201], v[50:53]
	v_mfma_f32_16x16x32_bf16 v[34:37], v[190:193], v[206:209], v[34:37]
	v_mfma_f32_16x16x32_bf16 v[38:41], v[182:185], v[206:209], v[38:41]
	v_mfma_f32_16x16x32_bf16 v[22:25], v[182:185], v[214:217], v[22:25]
	v_mfma_f32_16x16x32_bf16 v[18:21], v[190:193], v[214:217], v[18:21]
	v_mfma_f32_16x16x32_bf16 v[2:5], v[190:193], v[222:225], v[2:5]
	v_mfma_f32_16x16x32_bf16 v[6:9], v[182:185], v[222:225], v[6:9]
	s_barrier
; #define PG8_STAGE(bufoff, gbase, voff) do { _Pragma("unroll") for (int _i = 0; _i < 2; ++_i) \
;         __builtin_amdgcn_global_load_lds((const unsigned*)((const char*)(gbase) + (voff)[_i]), (PG8_LAS unsigned*)(lds + (bufoff) + ldsw + _i * 8192), 16, 0, 0); } while (0)
; #define PG8_LDA(dst, b, h) do { _Pragma("unroll") for (int m = 0; m < 4; ++m) _Pragma("unroll") for (int k = 0; k < 2; ++k) dst[m][k] = *(const PG8_LAS bf16x8*)(lds + PG8_SA(b, h) + aoff + m * 2048 + k * 1024); } while (0)
; #define PG8_LDB(dst, b, h) do { _Pragma("unroll") for (int n = 0; n < 2; ++n) _Pragma("unroll") for (int k = 0; k < 2; ++k) dst[n][k] = *(const PG8_LAS bf16x8*)(lds + PG8_SB(b, h) + boff + n * 2048 + k * 1024); } while (0)
; #define PG8_MMA(ai, bj, At, Bt) do { __builtin_amdgcn_s_setprio(1); _Pragma("unroll") for (int m = 0; m < 4; ++m) _Pragma("unroll") for (int n = 0; n < 2; ++n) _Pragma("unroll") for (int k = 0; k < 2; ++k) \
;         acc[ai][bj][m][n] = __builtin_amdgcn_mfma_f32_16x16x32_bf16(Bt[n][k], At[m][k], acc[ai][bj][m][n], 0, 0, 0); __builtin_amdgcn_s_setprio(0); } while (0)
; #define PG8_WAIT_V(n) asm volatile("s_waitcnt vmcnt(" #n ")" ::: "memory")
; #define PG8_WAIT_L(n) asm volatile("s_waitcnt lgkmcnt(" #n ")" ::: "memory")
; #define PG8_BAR __builtin_amdgcn_s_barrier()
; #define PG8_SCHED __builtin_amdgcn_sched_barrier(0)
; template <class Epi, class Sched, bool ALIGN_EPI = false, bool SP2 = false>
; __device__ __forceinline__ void gemm_phase(PG8_LAS unsigned char* lds, const Gemm g, const Sched& S, const Epi& E) {
;     ...
;         for (int t = 0; t < nt; t += 2) {
;     ...
;             PG8_LDB(B0, 1, 0); PG8_LDB(B1, 1, 1); PG8_SCHED; PG8_LDA(At, 1, 0); PG8_STAGE(PG8_SA(0, 1), a2 + hstep, voffA);
;             PG8_WAIT_V(8); PG8_WAIT_L(0); PG8_BAR; PG8_MMA(0, 0, At, B0); PG8_MMA(0, 1, At, B1); PG8_BAR; PG8_SCHED;
;             PG8_LDA(At, 1, 1); PG8_STAGE(PG8_SB(1, 0), b3, voffB); PG8_STAGE(PG8_SB(1, 1), b3 + hstep, voffB); PG8_STAGE(PG8_SA(1, 0), a3, voffA);
;             PG8_WAIT_V(8); PG8_WAIT_L(0); PG8_BAR; PG8_MMA(1, 0, At, B0); PG8_MMA(1, 1, At, B1); PG8_BAR; PG8_SCHED;
	s_setprio 0
	s_add_i32 s64, 16, 0x18000
	s_add_i32 s65, 16, 0x1c000
	v_add_u32_e32 v142, s64, v179
	v_add_u32_e32 v190, s65, v179
	ds_read_b128 v[130:133], v142
	ds_read_b128 v[134:137], v142 offset:1024
	ds_read_b128 v[138:141], v142 offset:2048
	ds_read_b128 v[142:145], v142 offset:3072
	ds_read_b128 v[158:161], v190
	ds_read_b128 v[182:185], v190 offset:1024
	ds_read_b128 v[186:189], v190 offset:2048
	ds_read_b128 v[190:193], v190 offset:3072
	s_add_u32 s10, s50, 0x40000
	s_addc_u32 s11, s51, 0
	s_mov_b32 m0, s6
	ds_read_b128 v[194:197], v181 offset:32768
	ds_read_b128 v[198:201], v181 offset:33792
	ds_read_b128 v[202:205], v181 offset:34816
	ds_read_b128 v[206:209], v181 offset:35840
	ds_read_b128 v[210:213], v181 offset:36864
	ds_read_b128 v[214:217], v181 offset:37888
	ds_read_b128 v[218:221], v181 offset:38912
	ds_read_b128 v[222:225], v181 offset:39936
	global_load_lds_dwordx4 v150, s[10:11]
	s_mov_b32 m0, s7
	s_nop 0
	global_load_lds_dwordx4 v148, s[10:11]
	s_waitcnt vmcnt(8)
	s_waitcnt lgkmcnt(0)
	s_setprio 1
	s_barrier
	v_mfma_f32_16x16x32_bf16 v[126:129], v[130:133], v[194:197], v[126:129]
	v_mfma_f32_16x16x32_bf16 v[122:125], v[138:141], v[194:197], v[122:125]
	v_mfma_f32_16x16x32_bf16 v[106:109], v[138:141], v[202:205], v[106:109]
	v_mfma_f32_16x16x32_bf16 v[110:113], v[130:133], v[202:205], v[110:113]
	v_mfma_f32_16x16x32_bf16 v[94:97], v[130:133], v[210:213], v[94:97]
	v_mfma_f32_16x16x32_bf16 v[90:93], v[138:141], v[210:213], v[90:93]
	v_mfma_f32_16x16x32_bf16 v[74:77], v[138:141], v[218:221], v[74:77]
	v_mfma_f32_16x16x32_bf16 v[78:81], v[130:133], v[218:221], v[78:81]
	v_mfma_f32_16x16x32_bf16 v[126:129], v[134:137], v[198:201], v[126:129]
	v_mfma_f32_16x16x32_bf16 v[122:125], v[142:145], v[198:201], v[122:125]
	v_mfma_f32_16x16x32_bf16 v[106:109], v[142:145], v[206:209], v[106:109]
	v_mfma_f32_16x16x32_bf16 v[110:113], v[134:137], v[206:209], v[110:113]
	v_mfma_f32_16x16x32_bf16 v[94:97], v[134:137], v[214:217], v[94:97]
	v_mfma_f32_16x16x32_bf16 v[90:93], v[142:145], v[214:217], v[90:93]
	v_mfma_f32_16x16x32_bf16 v[74:77], v[142:145], v[222:225], v[74:77]
	v_mfma_f32_16x16x32_bf16 v[78:81], v[134:137], v[222:225], v[78:81]
	v_mfma_f32_16x16x32_bf16 v[118:121], v[158:161], v[194:197], v[118:121]
	v_mfma_f32_16x16x32_bf16 v[114:117], v[186:189], v[194:197], v[114:117]
	v_mfma_f32_16x16x32_bf16 v[98:101], v[186:189], v[202:205], v[98:101]
	v_mfma_f32_16x16x32_bf16 v[102:105], v[158:161], v[202:205], v[102:105]
	v_mfma_f32_16x16x32_bf16 v[86:89], v[158:161], v[210:213], v[86:89]
	v_mfma_f32_16x16x32_bf16 v[82:85], v[186:189], v[210:213], v[82:85]
	v_mfma_f32_16x16x32_bf16 v[66:69], v[186:189], v[218:221], v[66:69]
	v_mfma_f32_16x16x32_bf16 v[70:73], v[158:161], v[218:221], v[70:73]
	v_mfma_f32_16x16x32_bf16 v[118:121], v[182:185], v[198:201], v[118:121]
	v_mfma_f32_16x16x32_bf16 v[114:117], v[190:193], v[198:201], v[114:117]
	v_mfma_f32_16x16x32_bf16 v[98:101], v[190:193], v[206:209], v[98:101]
	v_mfma_f32_16x16x32_bf16 v[102:105], v[182:185], v[206:209], v[102:105]
	v_mfma_f32_16x16x32_bf16 v[86:89], v[182:185], v[214:217], v[86:89]
	v_mfma_f32_16x16x32_bf16 v[82:85], v[190:193], v[214:217], v[82:85]
	v_mfma_f32_16x16x32_bf16 v[66:69], v[190:193], v[222:225], v[66:69]
	v_mfma_f32_16x16x32_bf16 v[70:73], v[182:185], v[222:225], v[70:73]
	s_barrier
	s_setprio 0
	s_add_i32 s10, s64, s3
	s_add_u32 s98, s48, s28
	s_addc_u32 s99, s49, s29
	s_mov_b32 m0, s10
	ds_read_b128 v[194:197], v181 offset:49152
	ds_read_b128 v[198:201], v181 offset:50176
	ds_read_b128 v[202:205], v181 offset:51200
	ds_read_b128 v[206:209], v181 offset:52224
	ds_read_b128 v[210:213], v181 offset:53248
	ds_read_b128 v[214:217], v181 offset:54272
	ds_read_b128 v[218:221], v181 offset:55296
	ds_read_b128 v[222:225], v181 offset:56320
	global_load_lds_dwordx4 v0, s[98:99]
	s_add_i32 m0, s10, 0x2000
	s_add_u32 s10, s48, 0x40080
	s_addc_u32 s11, s49, 0
	s_add_u32 s100, s48, s28
	s_addc_u32 s101, s49, s29
	s_add_i32 s48, s65, s3
	global_load_lds_dwordx4 v146, s[100:101]
	s_mov_b32 m0, s48
	s_nop 0
	global_load_lds_dwordx4 v0, s[10:11]
	s_add_i32 m0, s48, 0x2000
	s_nop 0
	global_load_lds_dwordx4 v146, s[10:11]
	s_add_u32 s98, s50, s28
	s_addc_u32 s99, s51, s29
	s_mov_b32 m0, s54
	s_nop 0
	global_load_lds_dwordx4 v150, s[98:99]
	s_add_u32 s100, s50, s28
	s_addc_u32 s101, s51, s29
	s_mov_b32 m0, s55
	s_nop 0
	global_load_lds_dwordx4 v148, s[100:101]
	s_waitcnt vmcnt(8)
	s_waitcnt lgkmcnt(0)
	s_setprio 1
	s_barrier
	v_mfma_f32_16x16x32_bf16 v[62:65], v[130:133], v[194:197], v[62:65]
	v_mfma_f32_16x16x32_bf16 v[58:61], v[138:141], v[194:197], v[58:61]
	v_mfma_f32_16x16x32_bf16 v[42:45], v[138:141], v[202:205], v[42:45]
	v_mfma_f32_16x16x32_bf16 v[46:49], v[130:133], v[202:205], v[46:49]
	v_mfma_f32_16x16x32_bf16 v[30:33], v[130:133], v[210:213], v[30:33]
	v_mfma_f32_16x16x32_bf16 v[26:29], v[138:141], v[210:213], v[26:29]
	v_mfma_f32_16x16x32_bf16 v[10:13], v[138:141], v[218:221], v[10:13]
	v_mfma_f32_16x16x32_bf16 v[14:17], v[130:133], v[218:221], v[14:17]
	v_mfma_f32_16x16x32_bf16 v[62:65], v[134:137], v[198:201], v[62:65]
	v_mfma_f32_16x16x32_bf16 v[58:61], v[142:145], v[198:201], v[58:61]
	v_mfma_f32_16x16x32_bf16 v[42:45], v[142:145], v[206:209], v[42:45]
	v_mfma_f32_16x16x32_bf16 v[46:49], v[134:137], v[206:209], v[46:49]
	v_mfma_f32_16x16x32_bf16 v[30:33], v[134:137], v[214:217], v[30:33]
	v_mfma_f32_16x16x32_bf16 v[26:29], v[142:145], v[214:217], v[26:29]
	v_mfma_f32_16x16x32_bf16 v[10:13], v[142:145], v[222:225], v[10:13]
	v_mfma_f32_16x16x32_bf16 v[14:17], v[134:137], v[222:225], v[14:17]
	v_mfma_f32_16x16x32_bf16 v[54:57], v[158:161], v[194:197], v[54:57]
	v_mfma_f32_16x16x32_bf16 v[50:53], v[186:189], v[194:197], v[50:53]
	v_mfma_f32_16x16x32_bf16 v[34:37], v[186:189], v[202:205], v[34:37]
	v_mfma_f32_16x16x32_bf16 v[38:41], v[158:161], v[202:205], v[38:41]
	v_mfma_f32_16x16x32_bf16 v[22:25], v[158:161], v[210:213], v[22:25]
	v_mfma_f32_16x16x32_bf16 v[18:21], v[186:189], v[210:213], v[18:21]
	v_mfma_f32_16x16x32_bf16 v[2:5], v[186:189], v[218:221], v[2:5]
	v_mfma_f32_16x16x32_bf16 v[6:9], v[158:161], v[218:221], v[6:9]
	v_mfma_f32_16x16x32_bf16 v[54:57], v[182:185], v[198:201], v[54:57]
	v_mfma_f32_16x16x32_bf16 v[50:53], v[190:193], v[198:201], v[50:53]
	v_mfma_f32_16x16x32_bf16 v[34:37], v[190:193], v[206:209], v[34:37]
	v_mfma_f32_16x16x32_bf16 v[38:41], v[182:185], v[206:209], v[38:41]
	v_mfma_f32_16x16x32_bf16 v[22:25], v[182:185], v[214:217], v[22:25]
	v_mfma_f32_16x16x32_bf16 v[18:21], v[190:193], v[214:217], v[18:21]
	v_mfma_f32_16x16x32_bf16 v[2:5], v[190:193], v[222:225], v[2:5]
	v_mfma_f32_16x16x32_bf16 v[6:9], v[182:185], v[222:225], v[6:9]
	s_barrier
	s_setprio 0
	s_add_i32 s63, s63, 2
	s_add_u32 s59, s59, 0x100
	s_addc_u32 s62, s62, 0
	s_add_u32 s40, s40, 0x100
	s_addc_u32 s41, s41, 0
	s_cmp_gt_u32 s63, 13
	s_cbranch_scc0 .LBB0_1275
	s_and_b64 vcc, exec, s[24:25]
	s_cbranch_vccz .LBB0_1278
	s_barrier
